# also P10/P13/P16 residual epilogues as rolling prefetch pipelines
# speedup vs baseline: 1.0132x; 1.0022x over previous
.LBB0_1460:
	ds_read_b128 v[144:147], v155
	ds_read_b128 v[148:151], v155 offset:1024
	ds_read_b128 v[158:161], v155 offset:2048
	ds_read_b128 v[162:165], v155 offset:3072
	s_add_u32 s33, s52, 0x4000
	s_addc_u32 s54, s53, 0
	s_cmp_eq_u32 s86, 60
	s_cselect_b32 s58, s82, s33
	s_cselect_b32 s59, s37, s54
	s_cselect_b32 s54, s83, s84
	s_cselect_b32 s55, s35, s85
	s_add_u32 s56, s58, 0x8000
	s_addc_u32 s57, s59, 0
	v_lshl_add_u64 v[206:207], s[52:53], 0, v[138:139]
	s_add_i32 m0, s64, 0xc000
	ds_read_b128 v[166:169], v156
	ds_read_b128 v[178:181], v156 offset:1024
	ds_read_b128 v[182:185], v156 offset:2048
	ds_read_b128 v[186:189], v156 offset:3072
	ds_read_b128 v[190:193], v156 offset:4096
	ds_read_b128 v[194:197], v156 offset:5120
	ds_read_b128 v[198:201], v156 offset:6144
	ds_read_b128 v[202:205], v156 offset:7168
	global_load_lds_dwordx4 v[206:207], off
	v_lshl_add_u64 v[206:207], s[52:53], 0, v[136:137]
	s_add_i32 m0, s64, 0xe000
	s_nop 0
	global_load_lds_dwordx4 v[206:207], off
	s_waitcnt lgkmcnt(8)
	s_barrier
	s_waitcnt lgkmcnt(0)
	s_setprio 1
	s_waitcnt lgkmcnt(0)
	v_mfma_f32_16x16x32_bf16 v[124:127], v[144:147], v[166:169], v[124:127]
	v_mfma_f32_16x16x32_bf16 v[120:123], v[158:161], v[166:169], v[120:123]
	v_mfma_f32_16x16x32_bf16 v[108:111], v[144:147], v[182:185], v[108:111]
	v_mfma_f32_16x16x32_bf16 v[104:107], v[158:161], v[182:185], v[104:107]
	v_mfma_f32_16x16x32_bf16 v[92:95], v[144:147], v[190:193], v[92:95]
	v_mfma_f32_16x16x32_bf16 v[88:91], v[158:161], v[190:193], v[88:91]
	v_mfma_f32_16x16x32_bf16 v[76:79], v[144:147], v[198:201], v[76:79]
	v_mfma_f32_16x16x32_bf16 v[72:75], v[158:161], v[198:201], v[72:75]
	v_mfma_f32_16x16x32_bf16 v[124:127], v[148:151], v[178:181], v[124:127]
	v_mfma_f32_16x16x32_bf16 v[120:123], v[162:165], v[178:181], v[120:123]
	v_mfma_f32_16x16x32_bf16 v[108:111], v[148:151], v[186:189], v[108:111]
	v_mfma_f32_16x16x32_bf16 v[104:107], v[162:165], v[186:189], v[104:107]
	v_mfma_f32_16x16x32_bf16 v[92:95], v[148:151], v[194:197], v[92:95]
	v_mfma_f32_16x16x32_bf16 v[88:91], v[162:165], v[194:197], v[88:91]
	v_mfma_f32_16x16x32_bf16 v[76:79], v[148:151], v[202:205], v[76:79]
	v_mfma_f32_16x16x32_bf16 v[72:75], v[162:165], v[202:205], v[72:75]
	s_setprio 0
	s_barrier
	s_add_i32 s33, s74, s63
	v_lshl_add_u64 v[222:223], s[54:55], 0, v[132:133]
	s_mov_b32 m0, s33
	ds_read_b128 v[206:209], v157
	ds_read_b128 v[210:213], v157 offset:1024
	ds_read_b128 v[214:217], v157 offset:2048
	ds_read_b128 v[218:221], v157 offset:3072
	global_load_lds_dwordx4 v[222:223], off
	v_lshl_add_u64 v[224:225], s[54:55], 0, v[128:129]
	s_add_i32 m0, s33, 0x2000
	s_nop 0
	global_load_lds_dwordx4 v[224:225], off
	s_barrier
	s_waitcnt lgkmcnt(0)
	s_setprio 1
	s_waitcnt lgkmcnt(0)
	v_mfma_f32_16x16x32_bf16 v[116:119], v[206:209], v[166:169], v[116:119]
	v_mfma_f32_16x16x32_bf16 v[112:115], v[214:217], v[166:169], v[112:115]
	v_mfma_f32_16x16x32_bf16 v[100:103], v[206:209], v[182:185], v[100:103]
	v_mfma_f32_16x16x32_bf16 v[96:99], v[214:217], v[182:185], v[96:99]
	v_mfma_f32_16x16x32_bf16 v[84:87], v[206:209], v[190:193], v[84:87]
	v_mfma_f32_16x16x32_bf16 v[80:83], v[214:217], v[190:193], v[80:83]
	v_mfma_f32_16x16x32_bf16 v[68:71], v[206:209], v[198:201], v[68:71]
	v_mfma_f32_16x16x32_bf16 v[64:67], v[214:217], v[198:201], v[64:67]
	v_mfma_f32_16x16x32_bf16 v[116:119], v[210:213], v[178:181], v[116:119]
	v_mfma_f32_16x16x32_bf16 v[112:115], v[218:221], v[178:181], v[112:115]
	v_mfma_f32_16x16x32_bf16 v[100:103], v[210:213], v[186:189], v[100:103]
	v_mfma_f32_16x16x32_bf16 v[96:99], v[218:221], v[186:189], v[96:99]
	v_mfma_f32_16x16x32_bf16 v[84:87], v[210:213], v[194:197], v[84:87]
	v_mfma_f32_16x16x32_bf16 v[80:83], v[218:221], v[194:197], v[80:83]
	v_mfma_f32_16x16x32_bf16 v[68:71], v[210:213], v[202:205], v[68:71]
	v_mfma_f32_16x16x32_bf16 v[64:67], v[218:221], v[202:205], v[64:67]
	s_setprio 0
	s_mov_b32 m0, s64
	v_lshl_add_u64 v[226:227], s[58:59], 0, v[134:135]
	s_barrier
	ds_read_b128 v[166:169], v156 offset:16384
	ds_read_b128 v[178:181], v156 offset:17408
	ds_read_b128 v[182:185], v156 offset:18432
	ds_read_b128 v[186:189], v156 offset:19456
	ds_read_b128 v[190:193], v156 offset:20480
	ds_read_b128 v[194:197], v156 offset:21504
	ds_read_b128 v[198:201], v156 offset:22528
	ds_read_b128 v[202:205], v156 offset:23552
	global_load_lds_dwordx4 v[226:227], off
	v_lshl_add_u64 v[226:227], s[58:59], 0, v[130:131]
	s_mov_b32 m0, s65
	s_nop 0
	global_load_lds_dwordx4 v[226:227], off
	s_barrier
	s_waitcnt lgkmcnt(0)
	s_setprio 1
	s_waitcnt lgkmcnt(0)
	v_mfma_f32_16x16x32_bf16 v[60:63], v[144:147], v[166:169], v[60:63]
	v_mfma_f32_16x16x32_bf16 v[56:59], v[158:161], v[166:169], v[56:59]
	v_mfma_f32_16x16x32_bf16 v[44:47], v[144:147], v[182:185], v[44:47]
	v_mfma_f32_16x16x32_bf16 v[40:43], v[158:161], v[182:185], v[40:43]
	v_mfma_f32_16x16x32_bf16 v[28:31], v[144:147], v[190:193], v[28:31]
	v_mfma_f32_16x16x32_bf16 v[24:27], v[158:161], v[190:193], v[24:27]
	v_mfma_f32_16x16x32_bf16 v[12:15], v[144:147], v[198:201], v[12:15]
	v_mfma_f32_16x16x32_bf16 v[8:11], v[158:161], v[198:201], v[8:11]
	v_mfma_f32_16x16x32_bf16 v[60:63], v[148:151], v[178:181], v[60:63]
	v_mfma_f32_16x16x32_bf16 v[56:59], v[162:165], v[178:181], v[56:59]
	v_mfma_f32_16x16x32_bf16 v[44:47], v[148:151], v[186:189], v[44:47]
	v_mfma_f32_16x16x32_bf16 v[40:43], v[162:165], v[186:189], v[40:43]
	v_mfma_f32_16x16x32_bf16 v[28:31], v[148:151], v[194:197], v[28:31]
	v_mfma_f32_16x16x32_bf16 v[24:27], v[162:165], v[194:197], v[24:27]
	v_mfma_f32_16x16x32_bf16 v[12:15], v[148:151], v[202:205], v[12:15]
	v_mfma_f32_16x16x32_bf16 v[8:11], v[162:165], v[202:205], v[8:11]
	s_setprio 0
	s_barrier
	s_add_u32 s88, s54, 0x100000
	s_addc_u32 s89, s55, 0
	s_add_i32 s33, s75, s63
	v_lshl_add_u64 v[144:145], s[88:89], 0, v[132:133]
	s_mov_b32 m0, s33
	s_nop 0
	global_load_lds_dwordx4 v[144:145], off
	v_lshl_add_u64 v[144:145], s[88:89], 0, v[128:129]
	s_add_i32 m0, s33, 0x2000
	s_nop 0
	global_load_lds_dwordx4 v[144:145], off
	s_waitcnt vmcnt(6)
	s_barrier
	s_setprio 1
	v_mfma_f32_16x16x32_bf16 v[52:55], v[206:209], v[166:169], v[52:55]
	v_mfma_f32_16x16x32_bf16 v[48:51], v[214:217], v[166:169], v[48:51]
	v_mfma_f32_16x16x32_bf16 v[36:39], v[206:209], v[182:185], v[36:39]
	v_mfma_f32_16x16x32_bf16 v[32:35], v[214:217], v[182:185], v[32:35]
	v_mfma_f32_16x16x32_bf16 v[20:23], v[206:209], v[190:193], v[20:23]
	v_mfma_f32_16x16x32_bf16 v[16:19], v[214:217], v[190:193], v[16:19]
	v_mfma_f32_16x16x32_bf16 v[4:7], v[206:209], v[198:201], v[4:7]
	v_mfma_f32_16x16x32_bf16 v[0:3], v[214:217], v[198:201], v[0:3]
	v_mfma_f32_16x16x32_bf16 v[52:55], v[210:213], v[178:181], v[52:55]
	v_mfma_f32_16x16x32_bf16 v[48:51], v[218:221], v[178:181], v[48:51]
	v_mfma_f32_16x16x32_bf16 v[36:39], v[210:213], v[186:189], v[36:39]
	v_mfma_f32_16x16x32_bf16 v[32:35], v[218:221], v[186:189], v[32:35]
	v_mfma_f32_16x16x32_bf16 v[20:23], v[210:213], v[194:197], v[20:23]
	v_mfma_f32_16x16x32_bf16 v[16:19], v[218:221], v[194:197], v[16:19]
	v_mfma_f32_16x16x32_bf16 v[4:7], v[210:213], v[202:205], v[4:7]
	v_mfma_f32_16x16x32_bf16 v[0:3], v[218:221], v[202:205], v[0:3]
	s_setprio 0
	s_add_i32 s33, 0, 0x18000
	v_add_u32_e32 v162, s33, v153
	s_barrier
	ds_read_b128 v[144:147], v162
	ds_read_b128 v[148:151], v162 offset:1024
	ds_read_b128 v[158:161], v162 offset:2048
	ds_read_b128 v[162:165], v162 offset:3072
	s_add_u32 s58, s58, 0x4000
	s_addc_u32 s59, s59, 0
	s_mov_b32 m0, s66
	v_lshl_add_u64 v[206:207], s[58:59], 0, v[134:135]
	ds_read_b128 v[166:169], v156 offset:32768
	ds_read_b128 v[178:181], v156 offset:33792
	ds_read_b128 v[182:185], v156 offset:34816
	ds_read_b128 v[186:189], v156 offset:35840
	ds_read_b128 v[190:193], v156 offset:36864
	ds_read_b128 v[194:197], v156 offset:37888
	ds_read_b128 v[198:201], v156 offset:38912
	ds_read_b128 v[202:205], v156 offset:39936
	global_load_lds_dwordx4 v[206:207], off
	v_lshl_add_u64 v[206:207], s[58:59], 0, v[130:131]
	s_mov_b32 m0, s67
	s_nop 0
	global_load_lds_dwordx4 v[206:207], off
	s_waitcnt lgkmcnt(8)
	s_barrier
	s_waitcnt lgkmcnt(0)
	s_setprio 1
	s_waitcnt lgkmcnt(0)
	v_mfma_f32_16x16x32_bf16 v[124:127], v[144:147], v[166:169], v[124:127]
	v_mfma_f32_16x16x32_bf16 v[120:123], v[158:161], v[166:169], v[120:123]
	v_mfma_f32_16x16x32_bf16 v[108:111], v[144:147], v[182:185], v[108:111]
	v_mfma_f32_16x16x32_bf16 v[104:107], v[158:161], v[182:185], v[104:107]
	v_mfma_f32_16x16x32_bf16 v[92:95], v[144:147], v[190:193], v[92:95]
	v_mfma_f32_16x16x32_bf16 v[88:91], v[158:161], v[190:193], v[88:91]
	v_mfma_f32_16x16x32_bf16 v[76:79], v[144:147], v[198:201], v[76:79]
	v_mfma_f32_16x16x32_bf16 v[72:75], v[158:161], v[198:201], v[72:75]
	v_mfma_f32_16x16x32_bf16 v[124:127], v[148:151], v[178:181], v[124:127]
	v_mfma_f32_16x16x32_bf16 v[120:123], v[162:165], v[178:181], v[120:123]
	v_mfma_f32_16x16x32_bf16 v[108:111], v[148:151], v[186:189], v[108:111]
	v_mfma_f32_16x16x32_bf16 v[104:107], v[162:165], v[186:189], v[104:107]
	v_mfma_f32_16x16x32_bf16 v[92:95], v[148:151], v[194:197], v[92:95]
	v_mfma_f32_16x16x32_bf16 v[88:91], v[162:165], v[194:197], v[88:91]
	v_mfma_f32_16x16x32_bf16 v[76:79], v[148:151], v[202:205], v[76:79]
	v_mfma_f32_16x16x32_bf16 v[72:75], v[162:165], v[202:205], v[72:75]
	s_setprio 0
	s_barrier
	s_add_i32 s58, 0, 0x1c000
	s_add_i32 s33, s33, s63
	v_add_u32_e32 v177, s58, v153
	v_lshl_add_u64 v[222:223], v[222:223], 0, s[16:17]
	s_mov_b32 m0, s33
	ds_read_b128 v[206:209], v177
	ds_read_b128 v[210:213], v177 offset:1024
	ds_read_b128 v[214:217], v177 offset:2048
	ds_read_b128 v[218:221], v177 offset:3072
	global_load_lds_dwordx4 v[222:223], off
	v_lshl_add_u64 v[222:223], v[224:225], 0, s[16:17]
	s_add_i32 m0, s33, 0x2000
	s_nop 0
	global_load_lds_dwordx4 v[222:223], off
	s_barrier
	s_waitcnt lgkmcnt(0)
	s_setprio 1
	s_waitcnt lgkmcnt(0)
	v_mfma_f32_16x16x32_bf16 v[116:119], v[206:209], v[166:169], v[116:119]
	v_mfma_f32_16x16x32_bf16 v[112:115], v[214:217], v[166:169], v[112:115]
	v_mfma_f32_16x16x32_bf16 v[100:103], v[206:209], v[182:185], v[100:103]
	v_mfma_f32_16x16x32_bf16 v[96:99], v[214:217], v[182:185], v[96:99]
	v_mfma_f32_16x16x32_bf16 v[84:87], v[206:209], v[190:193], v[84:87]
	v_mfma_f32_16x16x32_bf16 v[80:83], v[214:217], v[190:193], v[80:83]
	v_mfma_f32_16x16x32_bf16 v[68:71], v[206:209], v[198:201], v[68:71]
	v_mfma_f32_16x16x32_bf16 v[64:67], v[214:217], v[198:201], v[64:67]
	v_mfma_f32_16x16x32_bf16 v[116:119], v[210:213], v[178:181], v[116:119]
	v_mfma_f32_16x16x32_bf16 v[112:115], v[218:221], v[178:181], v[112:115]
	v_mfma_f32_16x16x32_bf16 v[100:103], v[210:213], v[186:189], v[100:103]
	v_mfma_f32_16x16x32_bf16 v[96:99], v[218:221], v[186:189], v[96:99]
	v_mfma_f32_16x16x32_bf16 v[84:87], v[210:213], v[194:197], v[84:87]
	v_mfma_f32_16x16x32_bf16 v[80:83], v[218:221], v[194:197], v[80:83]
	v_mfma_f32_16x16x32_bf16 v[68:71], v[210:213], v[202:205], v[68:71]
	v_mfma_f32_16x16x32_bf16 v[64:67], v[218:221], v[202:205], v[64:67]
	s_setprio 0
	s_mov_b32 m0, s68
	v_lshl_add_u64 v[222:223], s[56:57], 0, v[134:135]
	s_barrier
	ds_read_b128 v[166:169], v156 offset:49152
	ds_read_b128 v[178:181], v156 offset:50176
	ds_read_b128 v[182:185], v156 offset:51200
	ds_read_b128 v[186:189], v156 offset:52224
	ds_read_b128 v[190:193], v156 offset:53248
	ds_read_b128 v[194:197], v156 offset:54272
	ds_read_b128 v[198:201], v156 offset:55296
	ds_read_b128 v[202:205], v156 offset:56320
	global_load_lds_dwordx4 v[222:223], off
	v_lshl_add_u64 v[222:223], s[56:57], 0, v[130:131]
	s_mov_b32 m0, s69
	s_nop 0
	global_load_lds_dwordx4 v[222:223], off
	s_barrier
	s_waitcnt lgkmcnt(0)
	s_setprio 1
	s_waitcnt lgkmcnt(0)
	v_mfma_f32_16x16x32_bf16 v[60:63], v[144:147], v[166:169], v[60:63]
	v_mfma_f32_16x16x32_bf16 v[56:59], v[158:161], v[166:169], v[56:59]
	v_mfma_f32_16x16x32_bf16 v[44:47], v[144:147], v[182:185], v[44:47]
	v_mfma_f32_16x16x32_bf16 v[40:43], v[158:161], v[182:185], v[40:43]
	v_mfma_f32_16x16x32_bf16 v[28:31], v[144:147], v[190:193], v[28:31]
	v_mfma_f32_16x16x32_bf16 v[24:27], v[158:161], v[190:193], v[24:27]
	v_mfma_f32_16x16x32_bf16 v[12:15], v[144:147], v[198:201], v[12:15]
	v_mfma_f32_16x16x32_bf16 v[8:11], v[158:161], v[198:201], v[8:11]
	v_mfma_f32_16x16x32_bf16 v[60:63], v[148:151], v[178:181], v[60:63]
	v_mfma_f32_16x16x32_bf16 v[56:59], v[162:165], v[178:181], v[56:59]
	v_mfma_f32_16x16x32_bf16 v[44:47], v[148:151], v[186:189], v[44:47]
	v_mfma_f32_16x16x32_bf16 v[40:43], v[162:165], v[186:189], v[40:43]
	v_mfma_f32_16x16x32_bf16 v[28:31], v[148:151], v[194:197], v[28:31]
	v_mfma_f32_16x16x32_bf16 v[24:27], v[162:165], v[194:197], v[24:27]
	v_mfma_f32_16x16x32_bf16 v[12:15], v[148:151], v[202:205], v[12:15]
	v_mfma_f32_16x16x32_bf16 v[8:11], v[162:165], v[202:205], v[8:11]
	s_setprio 0
	s_barrier
	s_add_u32 s54, s54, 0x100080
	s_addc_u32 s55, s55, 0
	s_add_i32 s33, s58, s63
	v_lshl_add_u64 v[144:145], s[54:55], 0, v[132:133]
	s_mov_b32 m0, s33
	s_nop 0
	global_load_lds_dwordx4 v[144:145], off
	v_lshl_add_u64 v[144:145], s[54:55], 0, v[128:129]
	s_add_i32 m0, s33, 0x2000
	s_nop 0
	global_load_lds_dwordx4 v[144:145], off
	s_waitcnt vmcnt(6)
	s_barrier
	s_setprio 1
	v_mfma_f32_16x16x32_bf16 v[52:55], v[206:209], v[166:169], v[52:55]
	v_mfma_f32_16x16x32_bf16 v[48:51], v[214:217], v[166:169], v[48:51]
	v_mfma_f32_16x16x32_bf16 v[36:39], v[206:209], v[182:185], v[36:39]
	v_mfma_f32_16x16x32_bf16 v[32:35], v[214:217], v[182:185], v[32:35]
	v_mfma_f32_16x16x32_bf16 v[20:23], v[206:209], v[190:193], v[20:23]
	v_mfma_f32_16x16x32_bf16 v[16:19], v[214:217], v[190:193], v[16:19]
	v_mfma_f32_16x16x32_bf16 v[4:7], v[206:209], v[198:201], v[4:7]
	v_mfma_f32_16x16x32_bf16 v[0:3], v[214:217], v[198:201], v[0:3]
	v_mfma_f32_16x16x32_bf16 v[52:55], v[210:213], v[178:181], v[52:55]
	v_mfma_f32_16x16x32_bf16 v[48:51], v[218:221], v[178:181], v[48:51]
	v_mfma_f32_16x16x32_bf16 v[36:39], v[210:213], v[186:189], v[36:39]
	v_mfma_f32_16x16x32_bf16 v[32:35], v[218:221], v[186:189], v[32:35]
	v_mfma_f32_16x16x32_bf16 v[20:23], v[210:213], v[194:197], v[20:23]
	v_mfma_f32_16x16x32_bf16 v[16:19], v[218:221], v[194:197], v[16:19]
	v_mfma_f32_16x16x32_bf16 v[4:7], v[210:213], v[202:205], v[4:7]
	v_mfma_f32_16x16x32_bf16 v[0:3], v[218:221], v[202:205], v[0:3]
	s_setprio 0
	s_add_i32 s86, s86, 2
	s_add_u32 s84, s84, 0x100
	s_addc_u32 s85, s85, 0
	s_add_u32 s52, s52, 0x10000
	s_addc_u32 s53, s53, 0
	s_cmp_gt_u32 s86, 61
	s_barrier
	s_cbranch_scc0 .LBB0_1460
	s_lshl_b32 s82, s14, 8
	v_lshl_or_b32 v145, s81, 8, v154
	v_add_u32_e32 v144, s82, v152
	v_lshlrev_b32_e32 v145, 2, v145
	s_sub_u32 s83, s82, 0x1000
	s_lshr_b32 s83, s83, 11
	s_mul_i32 s83, s83, 6
	s_add_i32 s83, s83, 11
	s_cmp_gt_i32 s14, 15
	s_cselect_b32 s83, s83, 5
	s_lshl_b32 s83, s83, 12
	s_add_u32 s48, s72, s83
	s_addc_u32 s49, s73, 0
	v_lshl_add_u32 v146, v144, 12, v145
	global_load_dwordx4 v[148:151], v145, s[48:49]
	global_load_dwordx4 v[158:161], v145, s[48:49] offset:64
	global_load_dwordx4 v[162:165], v145, s[48:49] offset:512
	global_load_dwordx4 v[166:169], v145, s[48:49] offset:576
	s_mov_b64 s[84:85], s[24:25]
	s_mov_b64 s[86:87], s[24:25]
	global_load_dwordx4 v[178:181], v146, s[84:85]
	global_load_dwordx4 v[182:185], v146, s[84:85] offset:64
	global_load_dwordx4 v[186:189], v146, s[84:85] offset:512
	global_load_dwordx4 v[190:193], v146, s[84:85] offset:576
	s_add_u32 s84, s84, 0x10000
	s_addc_u32 s85, s85, 0
	global_load_dwordx4 v[194:197], v146, s[84:85]
	global_load_dwordx4 v[198:201], v146, s[84:85] offset:64
	global_load_dwordx4 v[202:205], v146, s[84:85] offset:512
	global_load_dwordx4 v[206:209], v146, s[84:85] offset:576
	s_add_u32 s84, s84, 0x10000
	s_addc_u32 s85, s85, 0
	global_load_dwordx4 v[210:213], v146, s[84:85]
	global_load_dwordx4 v[214:217], v146, s[84:85] offset:64
	global_load_dwordx4 v[218:221], v146, s[84:85] offset:512
	global_load_dwordx4 v[222:225], v146, s[84:85] offset:576
	s_add_u32 s84, s84, 0x10000
	s_addc_u32 s85, s85, 0
	global_load_dwordx4 v[226:229], v146, s[84:85]
	global_load_dwordx4 v[230:233], v146, s[84:85] offset:64
	s_waitcnt vmcnt(13)
	v_pk_fma_f32 v[124:125], v[124:125], v[148:149], v[178:179]
	v_pk_fma_f32 v[126:127], v[126:127], v[150:151], v[180:181]
	global_store_dwordx4 v146, v[124:127], s[86:87]
	global_load_dwordx4 v[178:181], v146, s[84:85] offset:512
	s_waitcnt vmcnt(14)
	v_pk_fma_f32 v[120:121], v[120:121], v[158:159], v[182:183]
	v_pk_fma_f32 v[122:123], v[122:123], v[160:161], v[184:185]
	global_store_dwordx4 v146, v[120:123], s[86:87] offset:64
	global_load_dwordx4 v[182:185], v146, s[84:85] offset:576
	s_waitcnt vmcnt(15)
	v_pk_fma_f32 v[116:117], v[116:117], v[162:163], v[186:187]
	v_pk_fma_f32 v[118:119], v[118:119], v[164:165], v[188:189]
	global_store_dwordx4 v146, v[116:119], s[86:87] offset:512
	s_add_u32 s84, s84, 0x50000
	s_addc_u32 s85, s85, 0
	global_load_dwordx4 v[186:189], v146, s[84:85]
	s_waitcnt vmcnt(16)
	v_pk_fma_f32 v[112:113], v[112:113], v[166:167], v[190:191]
	v_pk_fma_f32 v[114:115], v[114:115], v[168:169], v[192:193]
	global_store_dwordx4 v146, v[112:115], s[86:87] offset:576
	global_load_dwordx4 v[190:193], v146, s[84:85] offset:64
	s_add_u32 s86, s86, 0x10000
	s_addc_u32 s87, s87, 0
	s_waitcnt vmcnt(17)
	v_pk_fma_f32 v[108:109], v[108:109], v[148:149], v[194:195]
	v_pk_fma_f32 v[110:111], v[110:111], v[150:151], v[196:197]
	global_store_dwordx4 v146, v[108:111], s[86:87]
	global_load_dwordx4 v[194:197], v146, s[84:85] offset:512
	s_waitcnt vmcnt(18)
	v_pk_fma_f32 v[104:105], v[104:105], v[158:159], v[198:199]
	v_pk_fma_f32 v[106:107], v[106:107], v[160:161], v[200:201]
	global_store_dwordx4 v146, v[104:107], s[86:87] offset:64
	global_load_dwordx4 v[198:201], v146, s[84:85] offset:576
	s_waitcnt vmcnt(19)
	v_pk_fma_f32 v[100:101], v[100:101], v[162:163], v[202:203]
	v_pk_fma_f32 v[102:103], v[102:103], v[164:165], v[204:205]
	global_store_dwordx4 v146, v[100:103], s[86:87] offset:512
	s_add_u32 s84, s84, 0x10000
	s_addc_u32 s85, s85, 0
	global_load_dwordx4 v[202:205], v146, s[84:85]
	s_waitcnt vmcnt(20)
	v_pk_fma_f32 v[96:97], v[96:97], v[166:167], v[206:207]
	v_pk_fma_f32 v[98:99], v[98:99], v[168:169], v[208:209]
	global_store_dwordx4 v146, v[96:99], s[86:87] offset:576
	global_load_dwordx4 v[206:209], v146, s[84:85] offset:64
	s_add_u32 s86, s86, 0x10000
	s_addc_u32 s87, s87, 0
	s_waitcnt vmcnt(21)
	v_pk_fma_f32 v[92:93], v[92:93], v[148:149], v[210:211]
	v_pk_fma_f32 v[94:95], v[94:95], v[150:151], v[212:213]
	global_store_dwordx4 v146, v[92:95], s[86:87]
	global_load_dwordx4 v[210:213], v146, s[84:85] offset:512
	s_waitcnt vmcnt(22)
	v_pk_fma_f32 v[88:89], v[88:89], v[158:159], v[214:215]
	v_pk_fma_f32 v[90:91], v[90:91], v[160:161], v[216:217]
	global_store_dwordx4 v146, v[88:91], s[86:87] offset:64
	global_load_dwordx4 v[214:217], v146, s[84:85] offset:576
	s_waitcnt vmcnt(23)
	v_pk_fma_f32 v[84:85], v[84:85], v[162:163], v[218:219]
	v_pk_fma_f32 v[86:87], v[86:87], v[164:165], v[220:221]
	global_store_dwordx4 v146, v[84:87], s[86:87] offset:512
	s_add_u32 s84, s84, 0x10000
	s_addc_u32 s85, s85, 0
	global_load_dwordx4 v[218:221], v146, s[84:85]
	s_waitcnt vmcnt(24)
	v_pk_fma_f32 v[80:81], v[80:81], v[166:167], v[222:223]
	v_pk_fma_f32 v[82:83], v[82:83], v[168:169], v[224:225]
	global_store_dwordx4 v146, v[80:83], s[86:87] offset:576
	global_load_dwordx4 v[222:225], v146, s[84:85] offset:64
	s_add_u32 s86, s86, 0x10000
	s_addc_u32 s87, s87, 0
	s_waitcnt vmcnt(25)
	v_pk_fma_f32 v[76:77], v[76:77], v[148:149], v[226:227]
	v_pk_fma_f32 v[78:79], v[78:79], v[150:151], v[228:229]
	global_store_dwordx4 v146, v[76:79], s[86:87]
	global_load_dwordx4 v[226:229], v146, s[84:85] offset:512
	s_waitcnt vmcnt(26)
	v_pk_fma_f32 v[72:73], v[72:73], v[158:159], v[230:231]
	v_pk_fma_f32 v[74:75], v[74:75], v[160:161], v[232:233]
	global_store_dwordx4 v146, v[72:75], s[86:87] offset:64
	global_load_dwordx4 v[230:233], v146, s[84:85] offset:576
	s_waitcnt vmcnt(26)
	v_pk_fma_f32 v[68:69], v[68:69], v[162:163], v[178:179]
	v_pk_fma_f32 v[70:71], v[70:71], v[164:165], v[180:181]
	global_store_dwordx4 v146, v[68:71], s[86:87] offset:512
	s_add_u32 s84, s84, 0x10000
	s_addc_u32 s85, s85, 0
	global_load_dwordx4 v[178:181], v146, s[84:85]
	s_waitcnt vmcnt(26)
	v_pk_fma_f32 v[64:65], v[64:65], v[166:167], v[182:183]
	v_pk_fma_f32 v[66:67], v[66:67], v[168:169], v[184:185]
	global_store_dwordx4 v146, v[64:67], s[86:87] offset:576
	global_load_dwordx4 v[182:185], v146, s[84:85] offset:64
	s_add_u32 s86, s86, 0x50000
	s_addc_u32 s87, s87, 0
	s_waitcnt vmcnt(26)
	v_pk_fma_f32 v[60:61], v[60:61], v[148:149], v[186:187]
	v_pk_fma_f32 v[62:63], v[62:63], v[150:151], v[188:189]
	global_store_dwordx4 v146, v[60:63], s[86:87]
	global_load_dwordx4 v[186:189], v146, s[84:85] offset:512
	s_waitcnt vmcnt(26)
	v_pk_fma_f32 v[56:57], v[56:57], v[158:159], v[190:191]
	v_pk_fma_f32 v[58:59], v[58:59], v[160:161], v[192:193]
	global_store_dwordx4 v146, v[56:59], s[86:87] offset:64
	global_load_dwordx4 v[190:193], v146, s[84:85] offset:576
	s_waitcnt vmcnt(26)
	v_pk_fma_f32 v[52:53], v[52:53], v[162:163], v[194:195]
	v_pk_fma_f32 v[54:55], v[54:55], v[164:165], v[196:197]
	global_store_dwordx4 v146, v[52:55], s[86:87] offset:512
	s_waitcnt vmcnt(25)
	v_pk_fma_f32 v[48:49], v[48:49], v[166:167], v[198:199]
	v_pk_fma_f32 v[50:51], v[50:51], v[168:169], v[200:201]
	global_store_dwordx4 v146, v[48:51], s[86:87] offset:576
	s_add_u32 s86, s86, 0x10000
	s_addc_u32 s87, s87, 0
	s_waitcnt vmcnt(24)
	v_pk_fma_f32 v[44:45], v[44:45], v[148:149], v[202:203]
	v_pk_fma_f32 v[46:47], v[46:47], v[150:151], v[204:205]
	global_store_dwordx4 v146, v[44:47], s[86:87]
	s_waitcnt vmcnt(23)
	v_pk_fma_f32 v[40:41], v[40:41], v[158:159], v[206:207]
	v_pk_fma_f32 v[42:43], v[42:43], v[160:161], v[208:209]
	global_store_dwordx4 v146, v[40:43], s[86:87] offset:64
	s_waitcnt vmcnt(22)
	v_pk_fma_f32 v[36:37], v[36:37], v[162:163], v[210:211]
	v_pk_fma_f32 v[38:39], v[38:39], v[164:165], v[212:213]
	global_store_dwordx4 v146, v[36:39], s[86:87] offset:512
	s_waitcnt vmcnt(21)
	v_pk_fma_f32 v[32:33], v[32:33], v[166:167], v[214:215]
	v_pk_fma_f32 v[34:35], v[34:35], v[168:169], v[216:217]
	global_store_dwordx4 v146, v[32:35], s[86:87] offset:576
	s_add_u32 s86, s86, 0x10000
	s_addc_u32 s87, s87, 0
	s_waitcnt vmcnt(20)
	v_pk_fma_f32 v[28:29], v[28:29], v[148:149], v[218:219]
	v_pk_fma_f32 v[30:31], v[30:31], v[150:151], v[220:221]
	global_store_dwordx4 v146, v[28:31], s[86:87]
	s_waitcnt vmcnt(19)
	v_pk_fma_f32 v[24:25], v[24:25], v[158:159], v[222:223]
	v_pk_fma_f32 v[26:27], v[26:27], v[160:161], v[224:225]
	global_store_dwordx4 v146, v[24:27], s[86:87] offset:64
	s_waitcnt vmcnt(18)
	v_pk_fma_f32 v[20:21], v[20:21], v[162:163], v[226:227]
	v_pk_fma_f32 v[22:23], v[22:23], v[164:165], v[228:229]
	global_store_dwordx4 v146, v[20:23], s[86:87] offset:512
	s_waitcnt vmcnt(17)
	v_pk_fma_f32 v[16:17], v[16:17], v[166:167], v[230:231]
	v_pk_fma_f32 v[18:19], v[18:19], v[168:169], v[232:233]
	global_store_dwordx4 v146, v[16:19], s[86:87] offset:576
	s_add_u32 s86, s86, 0x10000
	s_addc_u32 s87, s87, 0
	s_waitcnt vmcnt(16)
	v_pk_fma_f32 v[12:13], v[12:13], v[148:149], v[178:179]
	v_pk_fma_f32 v[14:15], v[14:15], v[150:151], v[180:181]
	global_store_dwordx4 v146, v[12:15], s[86:87]
	s_waitcnt vmcnt(15)
	v_pk_fma_f32 v[8:9], v[8:9], v[158:159], v[182:183]
	v_pk_fma_f32 v[10:11], v[10:11], v[160:161], v[184:185]
	global_store_dwordx4 v146, v[8:11], s[86:87] offset:64
	s_waitcnt vmcnt(14)
	v_pk_fma_f32 v[4:5], v[4:5], v[162:163], v[186:187]
	v_pk_fma_f32 v[6:7], v[6:7], v[164:165], v[188:189]
	global_store_dwordx4 v146, v[4:7], s[86:87] offset:512
	s_waitcnt vmcnt(13)
	v_pk_fma_f32 v[0:1], v[0:1], v[166:167], v[190:191]
	v_pk_fma_f32 v[2:3], v[2:3], v[168:169], v[192:193]
	global_store_dwordx4 v146, v[0:3], s[86:87] offset:576
	s_mov_b32 s81, s34
	s_mov_b64 s[52:53], s[50:51]
	s_mov_b64 s[54:55], s[40:41]
	s_mov_b32 s14, s36
	s_and_b64 vcc, exec, s[12:13]
	s_cbranch_vccz .LBB0_1457
	s_waitcnt vmcnt(0)
	s_cmpk_gt_u32 s60, 0xff
	s_cbranch_scc1 .LBB0_1464
	s_barrier

.LBB0_1828:
	s_add_u32 s33, s56, s62
	s_addc_u32 s63, s57, 0
	s_add_u32 s66, s33, 0x100
	s_addc_u32 s67, s63, 0
	s_and_b64 s[64:65], s[60:61], exec
	s_cselect_b32 s67, s51, s67
	s_cselect_b32 s66, s50, s66
	s_add_u32 s62, s54, s62
	s_addc_u32 s64, s55, 0
	s_add_u32 s62, s62, 0x100
	s_addc_u32 s64, s64, 0
	s_and_b64 s[60:61], s[60:61], exec
	s_cselect_b32 s69, s37, s64
	s_cselect_b32 s68, s41, s62
	s_add_u32 s70, s33, 0x40080
	s_addc_u32 s71, s63, 0
	s_add_i32 s49, s84, s73
	s_add_i32 m0, s48, 0xc000
	s_add_i32 s74, s48, 0xe000
	s_add_i32 s33, s49, 0x2000
	s_add_u32 s64, s68, 0x10000
	s_addc_u32 s65, s69, 0
	s_add_i32 s97, s85, s73
	ds_read_b128 v[140:143], v149
	ds_read_b128 v[152:155], v149 offset:1024
	ds_read_b128 v[156:159], v149 offset:2048
	ds_read_b128 v[160:163], v149 offset:3072
	s_add_i32 s96, s97, 0x2000
	s_add_i32 s95, 0, 0x18000
	s_add_u32 s62, s66, 0x40000
	s_addc_u32 s63, s67, 0
	s_add_i32 s94, s95, s73
	s_add_i32 s93, 0, 0x1c000
	s_add_i32 s92, s94, 0x2000
	s_add_u32 s60, s68, 0x10080
	s_addc_u32 s61, s69, 0
	s_add_i32 vcc_hi, s93, s73
	s_add_i32 vcc_lo, vcc_hi, 0x2000
	v_lshl_add_u64 v[144:145], s[70:71], 0, v[134:135]
	ds_read_b128 v[164:167], v150
	ds_read_b128 v[178:181], v150 offset:1024
	ds_read_b128 v[182:185], v150 offset:2048
	ds_read_b128 v[186:189], v150 offset:3072
	ds_read_b128 v[190:193], v150 offset:4096
	ds_read_b128 v[194:197], v150 offset:5120
	ds_read_b128 v[198:201], v150 offset:6144
	ds_read_b128 v[202:205], v150 offset:7168
	global_load_lds_dwordx4 v[144:145], off
	v_lshl_add_u64 v[144:145], s[70:71], 0, v[130:131]
	s_mov_b32 m0, s74
	s_nop 0
	global_load_lds_dwordx4 v[144:145], off
	s_waitcnt lgkmcnt(8)
	s_barrier
	s_waitcnt lgkmcnt(0)
	s_setprio 1
	s_waitcnt lgkmcnt(0)
	v_mfma_f32_16x16x32_bf16 v[124:127], v[140:143], v[164:167], v[124:127]
	v_mfma_f32_16x16x32_bf16 v[120:123], v[156:159], v[164:167], v[120:123]
	v_mfma_f32_16x16x32_bf16 v[116:119], v[140:143], v[182:185], v[116:119]
	v_mfma_f32_16x16x32_bf16 v[112:115], v[156:159], v[182:185], v[112:115]
	v_mfma_f32_16x16x32_bf16 v[108:111], v[140:143], v[190:193], v[108:111]
	v_mfma_f32_16x16x32_bf16 v[104:107], v[156:159], v[190:193], v[104:107]
	v_mfma_f32_16x16x32_bf16 v[100:103], v[140:143], v[198:201], v[100:103]
	v_mfma_f32_16x16x32_bf16 v[96:99], v[156:159], v[198:201], v[96:99]
	v_mfma_f32_16x16x32_bf16 v[124:127], v[152:155], v[178:181], v[124:127]
	v_mfma_f32_16x16x32_bf16 v[120:123], v[160:163], v[178:181], v[120:123]
	v_mfma_f32_16x16x32_bf16 v[116:119], v[152:155], v[186:189], v[116:119]
	v_mfma_f32_16x16x32_bf16 v[112:115], v[160:163], v[186:189], v[112:115]
	v_mfma_f32_16x16x32_bf16 v[108:111], v[152:155], v[194:197], v[108:111]
	v_mfma_f32_16x16x32_bf16 v[104:107], v[160:163], v[194:197], v[104:107]
	v_mfma_f32_16x16x32_bf16 v[100:103], v[152:155], v[202:205], v[100:103]
	v_mfma_f32_16x16x32_bf16 v[96:99], v[160:163], v[202:205], v[96:99]
	s_setprio 0
	s_barrier
	s_mov_b32 m0, s49
	v_lshl_add_u64 v[144:145], s[68:69], 0, v[132:133]
	ds_read_b128 v[206:209], v151
	ds_read_b128 v[210:213], v151 offset:1024
	ds_read_b128 v[214:217], v151 offset:2048
	ds_read_b128 v[218:221], v151 offset:3072
	global_load_lds_dwordx4 v[144:145], off
	v_lshl_add_u64 v[168:169], s[68:69], 0, v[128:129]
	s_mov_b32 m0, s33
	s_nop 0
	global_load_lds_dwordx4 v[168:169], off
	s_barrier
	s_waitcnt lgkmcnt(0)
	s_setprio 1
	s_waitcnt lgkmcnt(0)
	v_mfma_f32_16x16x32_bf16 v[92:95], v[206:209], v[164:167], v[92:95]
	v_mfma_f32_16x16x32_bf16 v[88:91], v[214:217], v[164:167], v[88:91]
	v_mfma_f32_16x16x32_bf16 v[84:87], v[206:209], v[182:185], v[84:87]
	v_mfma_f32_16x16x32_bf16 v[80:83], v[214:217], v[182:185], v[80:83]
	v_mfma_f32_16x16x32_bf16 v[76:79], v[206:209], v[190:193], v[76:79]
	v_mfma_f32_16x16x32_bf16 v[72:75], v[214:217], v[190:193], v[72:75]
	v_mfma_f32_16x16x32_bf16 v[68:71], v[206:209], v[198:201], v[68:71]
	v_mfma_f32_16x16x32_bf16 v[64:67], v[214:217], v[198:201], v[64:67]
	v_mfma_f32_16x16x32_bf16 v[92:95], v[210:213], v[178:181], v[92:95]
	v_mfma_f32_16x16x32_bf16 v[88:91], v[218:221], v[178:181], v[88:91]
	v_mfma_f32_16x16x32_bf16 v[84:87], v[210:213], v[186:189], v[84:87]
	v_mfma_f32_16x16x32_bf16 v[80:83], v[218:221], v[186:189], v[80:83]
	v_mfma_f32_16x16x32_bf16 v[76:79], v[210:213], v[194:197], v[76:79]
	v_mfma_f32_16x16x32_bf16 v[72:75], v[218:221], v[194:197], v[72:75]
	v_mfma_f32_16x16x32_bf16 v[68:71], v[210:213], v[202:205], v[68:71]
	v_mfma_f32_16x16x32_bf16 v[64:67], v[218:221], v[202:205], v[64:67]
	s_setprio 0
	s_mov_b32 m0, s48
	v_lshl_add_u64 v[222:223], s[66:67], 0, v[134:135]
	s_barrier
	ds_read_b128 v[164:167], v150 offset:16384
	ds_read_b128 v[178:181], v150 offset:17408
	ds_read_b128 v[182:185], v150 offset:18432
	ds_read_b128 v[186:189], v150 offset:19456
	ds_read_b128 v[190:193], v150 offset:20480
	ds_read_b128 v[194:197], v150 offset:21504
	ds_read_b128 v[198:201], v150 offset:22528
	ds_read_b128 v[202:205], v150 offset:23552
	global_load_lds_dwordx4 v[222:223], off
	v_lshl_add_u64 v[224:225], s[66:67], 0, v[130:131]
	s_mov_b32 m0, s75
	s_nop 0
	global_load_lds_dwordx4 v[224:225], off
	s_barrier
	s_waitcnt lgkmcnt(0)
	s_setprio 1
	s_waitcnt lgkmcnt(0)
	v_mfma_f32_16x16x32_bf16 v[60:63], v[140:143], v[164:167], v[60:63]
	v_mfma_f32_16x16x32_bf16 v[56:59], v[156:159], v[164:167], v[56:59]
	v_mfma_f32_16x16x32_bf16 v[52:55], v[140:143], v[182:185], v[52:55]
	v_mfma_f32_16x16x32_bf16 v[48:51], v[156:159], v[182:185], v[48:51]
	v_mfma_f32_16x16x32_bf16 v[44:47], v[140:143], v[190:193], v[44:47]
	v_mfma_f32_16x16x32_bf16 v[40:43], v[156:159], v[190:193], v[40:43]
	v_mfma_f32_16x16x32_bf16 v[36:39], v[140:143], v[198:201], v[36:39]
	v_mfma_f32_16x16x32_bf16 v[32:35], v[156:159], v[198:201], v[32:35]
	v_mfma_f32_16x16x32_bf16 v[60:63], v[152:155], v[178:181], v[60:63]
	v_mfma_f32_16x16x32_bf16 v[56:59], v[160:163], v[178:181], v[56:59]
	v_mfma_f32_16x16x32_bf16 v[52:55], v[152:155], v[186:189], v[52:55]
	v_mfma_f32_16x16x32_bf16 v[48:51], v[160:163], v[186:189], v[48:51]
	v_mfma_f32_16x16x32_bf16 v[44:47], v[152:155], v[194:197], v[44:47]
	v_mfma_f32_16x16x32_bf16 v[40:43], v[160:163], v[194:197], v[40:43]
	v_mfma_f32_16x16x32_bf16 v[36:39], v[152:155], v[202:205], v[36:39]
	v_mfma_f32_16x16x32_bf16 v[32:35], v[160:163], v[202:205], v[32:35]
	s_setprio 0
	s_barrier
	s_mov_b32 m0, s97
	v_lshl_add_u64 v[140:141], s[64:65], 0, v[132:133]
	global_load_lds_dwordx4 v[140:141], off
	v_lshl_add_u64 v[140:141], s[64:65], 0, v[128:129]
	s_mov_b32 m0, s96
	s_nop 0
	global_load_lds_dwordx4 v[140:141], off
	s_waitcnt vmcnt(6)
	s_barrier
	s_setprio 1
	v_mfma_f32_16x16x32_bf16 v[28:31], v[206:209], v[164:167], v[28:31]
	v_mfma_f32_16x16x32_bf16 v[24:27], v[214:217], v[164:167], v[24:27]
	v_mfma_f32_16x16x32_bf16 v[20:23], v[206:209], v[182:185], v[20:23]
	v_mfma_f32_16x16x32_bf16 v[16:19], v[214:217], v[182:185], v[16:19]
	v_mfma_f32_16x16x32_bf16 v[12:15], v[206:209], v[190:193], v[12:15]
	v_mfma_f32_16x16x32_bf16 v[8:11], v[214:217], v[190:193], v[8:11]
	v_mfma_f32_16x16x32_bf16 v[4:7], v[206:209], v[198:201], v[4:7]
	v_mfma_f32_16x16x32_bf16 v[0:3], v[214:217], v[198:201], v[0:3]
	v_mfma_f32_16x16x32_bf16 v[28:31], v[210:213], v[178:181], v[28:31]
	v_mfma_f32_16x16x32_bf16 v[24:27], v[218:221], v[178:181], v[24:27]
	v_mfma_f32_16x16x32_bf16 v[20:23], v[210:213], v[186:189], v[20:23]
	v_mfma_f32_16x16x32_bf16 v[16:19], v[218:221], v[186:189], v[16:19]
	v_mfma_f32_16x16x32_bf16 v[12:15], v[210:213], v[194:197], v[12:15]
	v_mfma_f32_16x16x32_bf16 v[8:11], v[218:221], v[194:197], v[8:11]
	v_mfma_f32_16x16x32_bf16 v[4:7], v[210:213], v[202:205], v[4:7]
	v_mfma_f32_16x16x32_bf16 v[0:3], v[218:221], v[202:205], v[0:3]
	s_setprio 0
	v_add_u32_e32 v160, s95, v147
	s_barrier
	ds_read_b128 v[140:143], v160
	ds_read_b128 v[152:155], v160 offset:1024
	ds_read_b128 v[156:159], v160 offset:2048
	ds_read_b128 v[160:163], v160 offset:3072
	s_mov_b32 m0, s76
	v_lshl_add_u64 v[206:207], s[62:63], 0, v[134:135]
	ds_read_b128 v[164:167], v150 offset:32768
	ds_read_b128 v[178:181], v150 offset:33792
	ds_read_b128 v[182:185], v150 offset:34816
	ds_read_b128 v[186:189], v150 offset:35840
	ds_read_b128 v[190:193], v150 offset:36864
	ds_read_b128 v[194:197], v150 offset:37888
	ds_read_b128 v[198:201], v150 offset:38912
	ds_read_b128 v[202:205], v150 offset:39936
	global_load_lds_dwordx4 v[206:207], off
	v_lshl_add_u64 v[206:207], s[62:63], 0, v[130:131]
	s_mov_b32 m0, s77
	s_nop 0
	global_load_lds_dwordx4 v[206:207], off
	s_waitcnt lgkmcnt(8)
	s_barrier
	s_waitcnt lgkmcnt(0)
	s_setprio 1
	s_waitcnt lgkmcnt(0)
	v_mfma_f32_16x16x32_bf16 v[124:127], v[140:143], v[164:167], v[124:127]
	v_mfma_f32_16x16x32_bf16 v[120:123], v[156:159], v[164:167], v[120:123]
	v_mfma_f32_16x16x32_bf16 v[116:119], v[140:143], v[182:185], v[116:119]
	v_mfma_f32_16x16x32_bf16 v[112:115], v[156:159], v[182:185], v[112:115]
	v_mfma_f32_16x16x32_bf16 v[108:111], v[140:143], v[190:193], v[108:111]
	v_mfma_f32_16x16x32_bf16 v[104:107], v[156:159], v[190:193], v[104:107]
	v_mfma_f32_16x16x32_bf16 v[100:103], v[140:143], v[198:201], v[100:103]
	v_mfma_f32_16x16x32_bf16 v[96:99], v[156:159], v[198:201], v[96:99]
	v_mfma_f32_16x16x32_bf16 v[124:127], v[152:155], v[178:181], v[124:127]
	v_mfma_f32_16x16x32_bf16 v[120:123], v[160:163], v[178:181], v[120:123]
	v_mfma_f32_16x16x32_bf16 v[116:119], v[152:155], v[186:189], v[116:119]
	v_mfma_f32_16x16x32_bf16 v[112:115], v[160:163], v[186:189], v[112:115]
	v_mfma_f32_16x16x32_bf16 v[108:111], v[152:155], v[194:197], v[108:111]
	v_mfma_f32_16x16x32_bf16 v[104:107], v[160:163], v[194:197], v[104:107]
	v_mfma_f32_16x16x32_bf16 v[100:103], v[152:155], v[202:205], v[100:103]
	v_mfma_f32_16x16x32_bf16 v[96:99], v[160:163], v[202:205], v[96:99]
	s_setprio 0
	s_barrier
	s_mov_b32 m0, s94
	v_add_u32_e32 v177, s93, v147
	v_lshl_add_u64 v[144:145], v[144:145], 0, s[24:25]
	ds_read_b128 v[206:209], v177
	ds_read_b128 v[210:213], v177 offset:1024
	ds_read_b128 v[214:217], v177 offset:2048
	ds_read_b128 v[218:221], v177 offset:3072
	global_load_lds_dwordx4 v[144:145], off
	v_lshl_add_u64 v[144:145], v[168:169], 0, s[24:25]
	s_mov_b32 m0, s92
	s_nop 0
	global_load_lds_dwordx4 v[144:145], off
	s_barrier
	s_waitcnt lgkmcnt(0)
	s_setprio 1
	s_waitcnt lgkmcnt(0)
	v_mfma_f32_16x16x32_bf16 v[92:95], v[206:209], v[164:167], v[92:95]
	v_mfma_f32_16x16x32_bf16 v[88:91], v[214:217], v[164:167], v[88:91]
	v_mfma_f32_16x16x32_bf16 v[84:87], v[206:209], v[182:185], v[84:87]
	v_mfma_f32_16x16x32_bf16 v[80:83], v[214:217], v[182:185], v[80:83]
	v_mfma_f32_16x16x32_bf16 v[76:79], v[206:209], v[190:193], v[76:79]
	v_mfma_f32_16x16x32_bf16 v[72:75], v[214:217], v[190:193], v[72:75]
	v_mfma_f32_16x16x32_bf16 v[68:71], v[206:209], v[198:201], v[68:71]
	v_mfma_f32_16x16x32_bf16 v[64:67], v[214:217], v[198:201], v[64:67]
	v_mfma_f32_16x16x32_bf16 v[92:95], v[210:213], v[178:181], v[92:95]
	v_mfma_f32_16x16x32_bf16 v[88:91], v[218:221], v[178:181], v[88:91]
	v_mfma_f32_16x16x32_bf16 v[84:87], v[210:213], v[186:189], v[84:87]
	v_mfma_f32_16x16x32_bf16 v[80:83], v[218:221], v[186:189], v[80:83]
	v_mfma_f32_16x16x32_bf16 v[76:79], v[210:213], v[194:197], v[76:79]
	v_mfma_f32_16x16x32_bf16 v[72:75], v[218:221], v[194:197], v[72:75]
	v_mfma_f32_16x16x32_bf16 v[68:71], v[210:213], v[202:205], v[68:71]
	v_mfma_f32_16x16x32_bf16 v[64:67], v[218:221], v[202:205], v[64:67]
	s_setprio 0
	s_mov_b32 m0, s78
	v_lshl_add_u64 v[144:145], v[222:223], 0, s[24:25]
	s_barrier
	ds_read_b128 v[164:167], v150 offset:49152
	ds_read_b128 v[178:181], v150 offset:50176
	ds_read_b128 v[182:185], v150 offset:51200
	ds_read_b128 v[186:189], v150 offset:52224
	ds_read_b128 v[190:193], v150 offset:53248
	ds_read_b128 v[194:197], v150 offset:54272
	ds_read_b128 v[198:201], v150 offset:55296
	ds_read_b128 v[202:205], v150 offset:56320
	global_load_lds_dwordx4 v[144:145], off
	v_lshl_add_u64 v[144:145], v[224:225], 0, s[24:25]
	s_mov_b32 m0, s79
	s_nop 0
	global_load_lds_dwordx4 v[144:145], off
	s_barrier
	s_waitcnt lgkmcnt(0)
	s_setprio 1
	s_waitcnt lgkmcnt(0)
	v_mfma_f32_16x16x32_bf16 v[60:63], v[140:143], v[164:167], v[60:63]
	v_mfma_f32_16x16x32_bf16 v[56:59], v[156:159], v[164:167], v[56:59]
	v_mfma_f32_16x16x32_bf16 v[52:55], v[140:143], v[182:185], v[52:55]
	v_mfma_f32_16x16x32_bf16 v[48:51], v[156:159], v[182:185], v[48:51]
	v_mfma_f32_16x16x32_bf16 v[44:47], v[140:143], v[190:193], v[44:47]
	v_mfma_f32_16x16x32_bf16 v[40:43], v[156:159], v[190:193], v[40:43]
	v_mfma_f32_16x16x32_bf16 v[36:39], v[140:143], v[198:201], v[36:39]
	v_mfma_f32_16x16x32_bf16 v[32:35], v[156:159], v[198:201], v[32:35]
	v_mfma_f32_16x16x32_bf16 v[60:63], v[152:155], v[178:181], v[60:63]
	v_mfma_f32_16x16x32_bf16 v[56:59], v[160:163], v[178:181], v[56:59]
	v_mfma_f32_16x16x32_bf16 v[52:55], v[152:155], v[186:189], v[52:55]
	v_mfma_f32_16x16x32_bf16 v[48:51], v[160:163], v[186:189], v[48:51]
	v_mfma_f32_16x16x32_bf16 v[44:47], v[152:155], v[194:197], v[44:47]
	v_mfma_f32_16x16x32_bf16 v[40:43], v[160:163], v[194:197], v[40:43]
	v_mfma_f32_16x16x32_bf16 v[36:39], v[152:155], v[202:205], v[36:39]
	v_mfma_f32_16x16x32_bf16 v[32:35], v[160:163], v[202:205], v[32:35]
	s_setprio 0
	s_barrier
	s_mov_b32 m0, vcc_hi
	v_lshl_add_u64 v[140:141], s[60:61], 0, v[132:133]
	global_load_lds_dwordx4 v[140:141], off
	v_lshl_add_u64 v[140:141], s[60:61], 0, v[128:129]
	s_mov_b32 m0, vcc_lo
	s_nop 0
	global_load_lds_dwordx4 v[140:141], off
	s_waitcnt vmcnt(6)
	s_barrier
	s_setprio 1
	v_mfma_f32_16x16x32_bf16 v[28:31], v[206:209], v[164:167], v[28:31]
	v_mfma_f32_16x16x32_bf16 v[24:27], v[214:217], v[164:167], v[24:27]
	v_mfma_f32_16x16x32_bf16 v[20:23], v[206:209], v[182:185], v[20:23]
	v_mfma_f32_16x16x32_bf16 v[16:19], v[214:217], v[182:185], v[16:19]
	v_mfma_f32_16x16x32_bf16 v[12:15], v[206:209], v[190:193], v[12:15]
	v_mfma_f32_16x16x32_bf16 v[8:11], v[214:217], v[190:193], v[8:11]
	v_mfma_f32_16x16x32_bf16 v[4:7], v[206:209], v[198:201], v[4:7]
	v_mfma_f32_16x16x32_bf16 v[0:3], v[214:217], v[198:201], v[0:3]
	v_mfma_f32_16x16x32_bf16 v[28:31], v[210:213], v[178:181], v[28:31]
	v_mfma_f32_16x16x32_bf16 v[24:27], v[218:221], v[178:181], v[24:27]
	v_mfma_f32_16x16x32_bf16 v[20:23], v[210:213], v[186:189], v[20:23]
	v_mfma_f32_16x16x32_bf16 v[16:19], v[218:221], v[186:189], v[16:19]
	v_mfma_f32_16x16x32_bf16 v[12:15], v[210:213], v[194:197], v[12:15]
	v_mfma_f32_16x16x32_bf16 v[8:11], v[218:221], v[194:197], v[8:11]
	v_mfma_f32_16x16x32_bf16 v[4:7], v[210:213], v[202:205], v[4:7]
	v_mfma_f32_16x16x32_bf16 v[0:3], v[218:221], v[202:205], v[0:3]
	s_setprio 0
	s_movk_i32 s62, 0x100
	s_andn2_b64 vcc, exec, s[58:59]
	s_mov_b64 s[60:61], -1
	s_mov_b64 s[58:59], 0
	s_barrier
	s_cbranch_vccz .LBB0_1828
	s_load_dwordx2 s[60:61], s[20:21], 0xc0
	s_lshl_b32 s68, s22, 8
	v_lshl_or_b32 v141, s91, 8, v148
	v_add_u32_e32 v140, s68, v146
	v_lshlrev_b32_e32 v141, 2, v141
	s_sub_u32 s69, s68, 0x1000
	s_lshr_b32 s69, s69, 11
	s_mul_i32 s69, s69, 6
	s_add_i32 s69, s69, 38
	s_cmp_gt_i32 s22, 15
	s_cselect_b32 s69, s69, 32
	s_lshl_b32 s69, s69, 12
	s_add_u32 s62, s82, s69
	s_addc_u32 s63, s83, 0
	v_lshl_add_u32 v142, v140, 12, v141
	global_load_dwordx4 v[152:155], v141, s[62:63]
	global_load_dwordx4 v[156:159], v141, s[62:63] offset:64
	global_load_dwordx4 v[160:163], v141, s[62:63] offset:512
	global_load_dwordx4 v[164:167], v141, s[62:63] offset:576
	s_waitcnt lgkmcnt(0)
	global_load_dwordx4 v[178:181], v141, s[60:61]
	global_load_dwordx4 v[182:185], v141, s[60:61] offset:64
	global_load_dwordx4 v[186:189], v141, s[60:61] offset:512
	global_load_dwordx4 v[190:193], v141, s[60:61] offset:576
	s_mov_b64 s[64:65], s[18:19]
	s_mov_b64 s[66:67], s[18:19]
	global_load_dwordx4 v[194:197], v142, s[64:65]
	global_load_dwordx4 v[198:201], v142, s[64:65] offset:64
	global_load_dwordx4 v[202:205], v142, s[64:65] offset:512
	global_load_dwordx4 v[206:209], v142, s[64:65] offset:576
	s_add_u32 s64, s64, 0x10000
	s_addc_u32 s65, s65, 0
	global_load_dwordx4 v[210:213], v142, s[64:65]
	global_load_dwordx4 v[214:217], v142, s[64:65] offset:64
	global_load_dwordx4 v[218:221], v142, s[64:65] offset:512
	global_load_dwordx4 v[222:225], v142, s[64:65] offset:576
	s_add_u32 s64, s64, 0x10000
	s_addc_u32 s65, s65, 0
	global_load_dwordx4 v[226:229], v142, s[64:65]
	global_load_dwordx4 v[230:233], v142, s[64:65] offset:64
	s_waitcnt vmcnt(9)
	v_pk_mul_f32 v[124:125], v[124:125], v[178:179]
	v_pk_mul_f32 v[126:127], v[126:127], v[180:181]
	v_pk_fma_f32 v[124:125], v[152:153], v[124:125], v[194:195]
	v_pk_fma_f32 v[126:127], v[154:155], v[126:127], v[196:197]
	global_store_dwordx4 v142, v[124:127], s[66:67]
	global_load_dwordx4 v[194:197], v142, s[64:65] offset:512
	s_waitcnt vmcnt(10)
	v_pk_mul_f32 v[120:121], v[120:121], v[182:183]
	v_pk_mul_f32 v[122:123], v[122:123], v[184:185]
	v_pk_fma_f32 v[120:121], v[156:157], v[120:121], v[198:199]
	v_pk_fma_f32 v[122:123], v[158:159], v[122:123], v[200:201]
	global_store_dwordx4 v142, v[120:123], s[66:67] offset:64
	global_load_dwordx4 v[198:201], v142, s[64:65] offset:576
	s_waitcnt vmcnt(11)
	v_pk_mul_f32 v[92:93], v[92:93], v[186:187]
	v_pk_mul_f32 v[94:95], v[94:95], v[188:189]
	v_pk_fma_f32 v[92:93], v[160:161], v[92:93], v[202:203]
	v_pk_fma_f32 v[94:95], v[162:163], v[94:95], v[204:205]
	global_store_dwordx4 v142, v[92:95], s[66:67] offset:512
	s_add_u32 s64, s64, 0x10000
	s_addc_u32 s65, s65, 0
	global_load_dwordx4 v[202:205], v142, s[64:65]
	s_waitcnt vmcnt(12)
	v_pk_mul_f32 v[88:89], v[88:89], v[190:191]
	v_pk_mul_f32 v[90:91], v[90:91], v[192:193]
	v_pk_fma_f32 v[88:89], v[164:165], v[88:89], v[206:207]
	v_pk_fma_f32 v[90:91], v[166:167], v[90:91], v[208:209]
	global_store_dwordx4 v142, v[88:91], s[66:67] offset:576
	global_load_dwordx4 v[206:209], v142, s[64:65] offset:64
	s_add_u32 s66, s66, 0x10000
	s_addc_u32 s67, s67, 0
	s_waitcnt vmcnt(13)
	v_pk_mul_f32 v[116:117], v[116:117], v[178:179]
	v_pk_mul_f32 v[118:119], v[118:119], v[180:181]
	v_pk_fma_f32 v[116:117], v[152:153], v[116:117], v[210:211]
	v_pk_fma_f32 v[118:119], v[154:155], v[118:119], v[212:213]
	global_store_dwordx4 v142, v[116:119], s[66:67]
	global_load_dwordx4 v[210:213], v142, s[64:65] offset:512
	s_waitcnt vmcnt(14)
	v_pk_mul_f32 v[112:113], v[112:113], v[182:183]
	v_pk_mul_f32 v[114:115], v[114:115], v[184:185]
	v_pk_fma_f32 v[112:113], v[156:157], v[112:113], v[214:215]
	v_pk_fma_f32 v[114:115], v[158:159], v[114:115], v[216:217]
	global_store_dwordx4 v142, v[112:115], s[66:67] offset:64
	global_load_dwordx4 v[214:217], v142, s[64:65] offset:576
	s_waitcnt vmcnt(15)
	v_pk_mul_f32 v[84:85], v[84:85], v[186:187]
	v_pk_mul_f32 v[86:87], v[86:87], v[188:189]
	v_pk_fma_f32 v[84:85], v[160:161], v[84:85], v[218:219]
	v_pk_fma_f32 v[86:87], v[162:163], v[86:87], v[220:221]
	global_store_dwordx4 v142, v[84:87], s[66:67] offset:512
	s_add_u32 s64, s64, 0x50000
	s_addc_u32 s65, s65, 0
	global_load_dwordx4 v[218:221], v142, s[64:65]
	s_waitcnt vmcnt(16)
	v_pk_mul_f32 v[80:81], v[80:81], v[190:191]
	v_pk_mul_f32 v[82:83], v[82:83], v[192:193]
	v_pk_fma_f32 v[80:81], v[164:165], v[80:81], v[222:223]
	v_pk_fma_f32 v[82:83], v[166:167], v[82:83], v[224:225]
	global_store_dwordx4 v142, v[80:83], s[66:67] offset:576
	global_load_dwordx4 v[222:225], v142, s[64:65] offset:64
	s_add_u32 s66, s66, 0x10000
	s_addc_u32 s67, s67, 0
	s_waitcnt vmcnt(17)
	v_pk_mul_f32 v[108:109], v[108:109], v[178:179]
	v_pk_mul_f32 v[110:111], v[110:111], v[180:181]
	v_pk_fma_f32 v[108:109], v[152:153], v[108:109], v[226:227]
	v_pk_fma_f32 v[110:111], v[154:155], v[110:111], v[228:229]
	global_store_dwordx4 v142, v[108:111], s[66:67]
	global_load_dwordx4 v[226:229], v142, s[64:65] offset:512
	s_waitcnt vmcnt(18)
	v_pk_mul_f32 v[104:105], v[104:105], v[182:183]
	v_pk_mul_f32 v[106:107], v[106:107], v[184:185]
	v_pk_fma_f32 v[104:105], v[156:157], v[104:105], v[230:231]
	v_pk_fma_f32 v[106:107], v[158:159], v[106:107], v[232:233]
	global_store_dwordx4 v142, v[104:107], s[66:67] offset:64
	global_load_dwordx4 v[230:233], v142, s[64:65] offset:576
	s_waitcnt vmcnt(18)
	v_pk_mul_f32 v[76:77], v[76:77], v[186:187]
	v_pk_mul_f32 v[78:79], v[78:79], v[188:189]
	v_pk_fma_f32 v[76:77], v[160:161], v[76:77], v[194:195]
	v_pk_fma_f32 v[78:79], v[162:163], v[78:79], v[196:197]
	global_store_dwordx4 v142, v[76:79], s[66:67] offset:512
	s_add_u32 s64, s64, 0x10000
	s_addc_u32 s65, s65, 0
	global_load_dwordx4 v[194:197], v142, s[64:65]
	s_waitcnt vmcnt(18)
	v_pk_mul_f32 v[72:73], v[72:73], v[190:191]
	v_pk_mul_f32 v[74:75], v[74:75], v[192:193]
	v_pk_fma_f32 v[72:73], v[164:165], v[72:73], v[198:199]
	v_pk_fma_f32 v[74:75], v[166:167], v[74:75], v[200:201]
	global_store_dwordx4 v142, v[72:75], s[66:67] offset:576
	global_load_dwordx4 v[198:201], v142, s[64:65] offset:64
	s_add_u32 s66, s66, 0x10000
	s_addc_u32 s67, s67, 0
	s_waitcnt vmcnt(18)
	v_pk_mul_f32 v[100:101], v[100:101], v[178:179]
	v_pk_mul_f32 v[102:103], v[102:103], v[180:181]
	v_pk_fma_f32 v[100:101], v[152:153], v[100:101], v[202:203]
	v_pk_fma_f32 v[102:103], v[154:155], v[102:103], v[204:205]
	global_store_dwordx4 v142, v[100:103], s[66:67]
	global_load_dwordx4 v[202:205], v142, s[64:65] offset:512
	s_waitcnt vmcnt(18)
	v_pk_mul_f32 v[96:97], v[96:97], v[182:183]
	v_pk_mul_f32 v[98:99], v[98:99], v[184:185]
	v_pk_fma_f32 v[96:97], v[156:157], v[96:97], v[206:207]
	v_pk_fma_f32 v[98:99], v[158:159], v[98:99], v[208:209]
	global_store_dwordx4 v142, v[96:99], s[66:67] offset:64
	global_load_dwordx4 v[206:209], v142, s[64:65] offset:576
	s_waitcnt vmcnt(18)
	v_pk_mul_f32 v[68:69], v[68:69], v[186:187]
	v_pk_mul_f32 v[70:71], v[70:71], v[188:189]
	v_pk_fma_f32 v[68:69], v[160:161], v[68:69], v[210:211]
	v_pk_fma_f32 v[70:71], v[162:163], v[70:71], v[212:213]
	global_store_dwordx4 v142, v[68:71], s[66:67] offset:512
	s_add_u32 s64, s64, 0x10000
	s_addc_u32 s65, s65, 0
	global_load_dwordx4 v[210:213], v142, s[64:65]
	s_waitcnt vmcnt(18)
	v_pk_mul_f32 v[64:65], v[64:65], v[190:191]
	v_pk_mul_f32 v[66:67], v[66:67], v[192:193]
	v_pk_fma_f32 v[64:65], v[164:165], v[64:65], v[214:215]
	v_pk_fma_f32 v[66:67], v[166:167], v[66:67], v[216:217]
	global_store_dwordx4 v142, v[64:67], s[66:67] offset:576
	global_load_dwordx4 v[214:217], v142, s[64:65] offset:64
	s_add_u32 s66, s66, 0x50000
	s_addc_u32 s67, s67, 0
	s_waitcnt vmcnt(18)
	v_pk_mul_f32 v[60:61], v[60:61], v[178:179]
	v_pk_mul_f32 v[62:63], v[62:63], v[180:181]
	v_pk_fma_f32 v[60:61], v[152:153], v[60:61], v[218:219]
	v_pk_fma_f32 v[62:63], v[154:155], v[62:63], v[220:221]
	global_store_dwordx4 v142, v[60:63], s[66:67]
	global_load_dwordx4 v[218:221], v142, s[64:65] offset:512
	s_waitcnt vmcnt(18)
	v_pk_mul_f32 v[56:57], v[56:57], v[182:183]
	v_pk_mul_f32 v[58:59], v[58:59], v[184:185]
	v_pk_fma_f32 v[56:57], v[156:157], v[56:57], v[222:223]
	v_pk_fma_f32 v[58:59], v[158:159], v[58:59], v[224:225]
	global_store_dwordx4 v142, v[56:59], s[66:67] offset:64
	global_load_dwordx4 v[222:225], v142, s[64:65] offset:576
	s_waitcnt vmcnt(18)
	v_pk_mul_f32 v[28:29], v[28:29], v[186:187]
	v_pk_mul_f32 v[30:31], v[30:31], v[188:189]
	v_pk_fma_f32 v[28:29], v[160:161], v[28:29], v[226:227]
	v_pk_fma_f32 v[30:31], v[162:163], v[30:31], v[228:229]
	global_store_dwordx4 v142, v[28:31], s[66:67] offset:512
	s_add_u32 s64, s64, 0x10000
	s_addc_u32 s65, s65, 0
	global_load_dwordx4 v[226:229], v142, s[64:65]
	s_waitcnt vmcnt(18)
	v_pk_mul_f32 v[24:25], v[24:25], v[190:191]
	v_pk_mul_f32 v[26:27], v[26:27], v[192:193]
	v_pk_fma_f32 v[24:25], v[164:165], v[24:25], v[230:231]
	v_pk_fma_f32 v[26:27], v[166:167], v[26:27], v[232:233]
	global_store_dwordx4 v142, v[24:27], s[66:67] offset:576
	global_load_dwordx4 v[230:233], v142, s[64:65] offset:64
	s_add_u32 s66, s66, 0x10000
	s_addc_u32 s67, s67, 0
	s_waitcnt vmcnt(18)
	v_pk_mul_f32 v[52:53], v[52:53], v[178:179]
	v_pk_mul_f32 v[54:55], v[54:55], v[180:181]
	v_pk_fma_f32 v[52:53], v[152:153], v[52:53], v[194:195]
	v_pk_fma_f32 v[54:55], v[154:155], v[54:55], v[196:197]
	global_store_dwordx4 v142, v[52:55], s[66:67]
	global_load_dwordx4 v[194:197], v142, s[64:65] offset:512
	s_waitcnt vmcnt(18)
	v_pk_mul_f32 v[48:49], v[48:49], v[182:183]
	v_pk_mul_f32 v[50:51], v[50:51], v[184:185]
	v_pk_fma_f32 v[48:49], v[156:157], v[48:49], v[198:199]
	v_pk_fma_f32 v[50:51], v[158:159], v[50:51], v[200:201]
	global_store_dwordx4 v142, v[48:51], s[66:67] offset:64
	global_load_dwordx4 v[198:201], v142, s[64:65] offset:576
	s_waitcnt vmcnt(18)
	v_pk_mul_f32 v[20:21], v[20:21], v[186:187]
	v_pk_mul_f32 v[22:23], v[22:23], v[188:189]
	v_pk_fma_f32 v[20:21], v[160:161], v[20:21], v[202:203]
	v_pk_fma_f32 v[22:23], v[162:163], v[22:23], v[204:205]
	global_store_dwordx4 v142, v[20:23], s[66:67] offset:512
	s_waitcnt vmcnt(17)
	v_pk_mul_f32 v[16:17], v[16:17], v[190:191]
	v_pk_mul_f32 v[18:19], v[18:19], v[192:193]
	v_pk_fma_f32 v[16:17], v[164:165], v[16:17], v[206:207]
	v_pk_fma_f32 v[18:19], v[166:167], v[18:19], v[208:209]
	global_store_dwordx4 v142, v[16:19], s[66:67] offset:576
	s_add_u32 s66, s66, 0x10000
	s_addc_u32 s67, s67, 0
	s_waitcnt vmcnt(16)
	v_pk_mul_f32 v[44:45], v[44:45], v[178:179]
	v_pk_mul_f32 v[46:47], v[46:47], v[180:181]
	v_pk_fma_f32 v[44:45], v[152:153], v[44:45], v[210:211]
	v_pk_fma_f32 v[46:47], v[154:155], v[46:47], v[212:213]
	global_store_dwordx4 v142, v[44:47], s[66:67]
	s_waitcnt vmcnt(15)
	v_pk_mul_f32 v[40:41], v[40:41], v[182:183]
	v_pk_mul_f32 v[42:43], v[42:43], v[184:185]
	v_pk_fma_f32 v[40:41], v[156:157], v[40:41], v[214:215]
	v_pk_fma_f32 v[42:43], v[158:159], v[42:43], v[216:217]
	global_store_dwordx4 v142, v[40:43], s[66:67] offset:64
	s_waitcnt vmcnt(14)
	v_pk_mul_f32 v[12:13], v[12:13], v[186:187]
	v_pk_mul_f32 v[14:15], v[14:15], v[188:189]
	v_pk_fma_f32 v[12:13], v[160:161], v[12:13], v[218:219]
	v_pk_fma_f32 v[14:15], v[162:163], v[14:15], v[220:221]
	global_store_dwordx4 v142, v[12:15], s[66:67] offset:512
	s_waitcnt vmcnt(13)
	v_pk_mul_f32 v[8:9], v[8:9], v[190:191]
	v_pk_mul_f32 v[10:11], v[10:11], v[192:193]
	v_pk_fma_f32 v[8:9], v[164:165], v[8:9], v[222:223]
	v_pk_fma_f32 v[10:11], v[166:167], v[10:11], v[224:225]
	global_store_dwordx4 v142, v[8:11], s[66:67] offset:576
	s_add_u32 s66, s66, 0x10000
	s_addc_u32 s67, s67, 0
	s_waitcnt vmcnt(12)
	v_pk_mul_f32 v[36:37], v[36:37], v[178:179]
	v_pk_mul_f32 v[38:39], v[38:39], v[180:181]
	v_pk_fma_f32 v[36:37], v[152:153], v[36:37], v[226:227]
	v_pk_fma_f32 v[38:39], v[154:155], v[38:39], v[228:229]
	global_store_dwordx4 v142, v[36:39], s[66:67]
	s_waitcnt vmcnt(11)
	v_pk_mul_f32 v[32:33], v[32:33], v[182:183]
	v_pk_mul_f32 v[34:35], v[34:35], v[184:185]
	v_pk_fma_f32 v[32:33], v[156:157], v[32:33], v[230:231]
	v_pk_fma_f32 v[34:35], v[158:159], v[34:35], v[232:233]
	global_store_dwordx4 v142, v[32:35], s[66:67] offset:64
	s_waitcnt vmcnt(10)
	v_pk_mul_f32 v[4:5], v[4:5], v[186:187]
	v_pk_mul_f32 v[6:7], v[6:7], v[188:189]
	v_pk_fma_f32 v[4:5], v[160:161], v[4:5], v[194:195]
	v_pk_fma_f32 v[6:7], v[162:163], v[6:7], v[196:197]
	global_store_dwordx4 v142, v[4:7], s[66:67] offset:512
	s_waitcnt vmcnt(9)
	v_pk_mul_f32 v[0:1], v[0:1], v[190:191]
	v_pk_mul_f32 v[2:3], v[2:3], v[192:193]
	v_pk_fma_f32 v[0:1], v[164:165], v[0:1], v[198:199]
	v_pk_fma_f32 v[2:3], v[166:167], v[2:3], v[200:201]
	global_store_dwordx4 v142, v[0:3], s[66:67] offset:576
	s_mov_b32 s91, s36
	s_mov_b64 s[54:55], s[52:53]
	s_mov_b64 s[56:57], s[50:51]
	s_mov_b32 s22, s40
	s_and_b64 vcc, exec, s[12:13]
	s_cbranch_vccz .LBB0_1823
	s_branch .LBB0_1832

.LBB0_2049:
	ds_read_b128 v[144:147], v155
	ds_read_b128 v[148:151], v155 offset:1024
	ds_read_b128 v[158:161], v155 offset:2048
	ds_read_b128 v[162:165], v155 offset:3072
	s_add_u32 s33, s40, 0x4000
	s_addc_u32 s48, s41, 0
	s_cmp_eq_u32 s80, 60
	s_cselect_b32 s52, s76, s33
	s_cselect_b32 s53, s31, s48
	s_cselect_b32 s48, s77, s78
	s_cselect_b32 s49, s29, s79
	s_add_u32 s50, s52, 0x8000
	s_addc_u32 s51, s53, 0
	v_lshl_add_u64 v[206:207], s[40:41], 0, v[138:139]
	s_add_i32 m0, s58, 0xc000
	ds_read_b128 v[166:169], v156
	ds_read_b128 v[178:181], v156 offset:1024
	ds_read_b128 v[182:185], v156 offset:2048
	ds_read_b128 v[186:189], v156 offset:3072
	ds_read_b128 v[190:193], v156 offset:4096
	ds_read_b128 v[194:197], v156 offset:5120
	ds_read_b128 v[198:201], v156 offset:6144
	ds_read_b128 v[202:205], v156 offset:7168
	global_load_lds_dwordx4 v[206:207], off
	v_lshl_add_u64 v[206:207], s[40:41], 0, v[136:137]
	s_add_i32 m0, s58, 0xe000
	s_nop 0
	global_load_lds_dwordx4 v[206:207], off
	s_waitcnt lgkmcnt(8)
	s_barrier
	s_waitcnt lgkmcnt(0)
	s_setprio 1
	s_waitcnt lgkmcnt(0)
	v_mfma_f32_16x16x32_bf16 v[124:127], v[144:147], v[166:169], v[124:127]
	v_mfma_f32_16x16x32_bf16 v[120:123], v[158:161], v[166:169], v[120:123]
	v_mfma_f32_16x16x32_bf16 v[108:111], v[144:147], v[182:185], v[108:111]
	v_mfma_f32_16x16x32_bf16 v[104:107], v[158:161], v[182:185], v[104:107]
	v_mfma_f32_16x16x32_bf16 v[92:95], v[144:147], v[190:193], v[92:95]
	v_mfma_f32_16x16x32_bf16 v[88:91], v[158:161], v[190:193], v[88:91]
	v_mfma_f32_16x16x32_bf16 v[76:79], v[144:147], v[198:201], v[76:79]
	v_mfma_f32_16x16x32_bf16 v[72:75], v[158:161], v[198:201], v[72:75]
	v_mfma_f32_16x16x32_bf16 v[124:127], v[148:151], v[178:181], v[124:127]
	v_mfma_f32_16x16x32_bf16 v[120:123], v[162:165], v[178:181], v[120:123]
	v_mfma_f32_16x16x32_bf16 v[108:111], v[148:151], v[186:189], v[108:111]
	v_mfma_f32_16x16x32_bf16 v[104:107], v[162:165], v[186:189], v[104:107]
	v_mfma_f32_16x16x32_bf16 v[92:95], v[148:151], v[194:197], v[92:95]
	v_mfma_f32_16x16x32_bf16 v[88:91], v[162:165], v[194:197], v[88:91]
	v_mfma_f32_16x16x32_bf16 v[76:79], v[148:151], v[202:205], v[76:79]
	v_mfma_f32_16x16x32_bf16 v[72:75], v[162:165], v[202:205], v[72:75]
	s_setprio 0
	s_barrier
	s_add_i32 s33, s68, s57
	v_lshl_add_u64 v[222:223], s[48:49], 0, v[132:133]
	s_mov_b32 m0, s33
	ds_read_b128 v[206:209], v157
	ds_read_b128 v[210:213], v157 offset:1024
	ds_read_b128 v[214:217], v157 offset:2048
	ds_read_b128 v[218:221], v157 offset:3072
	global_load_lds_dwordx4 v[222:223], off
	v_lshl_add_u64 v[224:225], s[48:49], 0, v[128:129]
	s_add_i32 m0, s33, 0x2000
	s_nop 0
	global_load_lds_dwordx4 v[224:225], off
	s_barrier
	s_waitcnt lgkmcnt(0)
	s_setprio 1
	s_waitcnt lgkmcnt(0)
	v_mfma_f32_16x16x32_bf16 v[116:119], v[206:209], v[166:169], v[116:119]
	v_mfma_f32_16x16x32_bf16 v[112:115], v[214:217], v[166:169], v[112:115]
	v_mfma_f32_16x16x32_bf16 v[100:103], v[206:209], v[182:185], v[100:103]
	v_mfma_f32_16x16x32_bf16 v[96:99], v[214:217], v[182:185], v[96:99]
	v_mfma_f32_16x16x32_bf16 v[84:87], v[206:209], v[190:193], v[84:87]
	v_mfma_f32_16x16x32_bf16 v[80:83], v[214:217], v[190:193], v[80:83]
	v_mfma_f32_16x16x32_bf16 v[68:71], v[206:209], v[198:201], v[68:71]
	v_mfma_f32_16x16x32_bf16 v[64:67], v[214:217], v[198:201], v[64:67]
	v_mfma_f32_16x16x32_bf16 v[116:119], v[210:213], v[178:181], v[116:119]
	v_mfma_f32_16x16x32_bf16 v[112:115], v[218:221], v[178:181], v[112:115]
	v_mfma_f32_16x16x32_bf16 v[100:103], v[210:213], v[186:189], v[100:103]
	v_mfma_f32_16x16x32_bf16 v[96:99], v[218:221], v[186:189], v[96:99]
	v_mfma_f32_16x16x32_bf16 v[84:87], v[210:213], v[194:197], v[84:87]
	v_mfma_f32_16x16x32_bf16 v[80:83], v[218:221], v[194:197], v[80:83]
	v_mfma_f32_16x16x32_bf16 v[68:71], v[210:213], v[202:205], v[68:71]
	v_mfma_f32_16x16x32_bf16 v[64:67], v[218:221], v[202:205], v[64:67]
	s_setprio 0
	s_mov_b32 m0, s58
	v_lshl_add_u64 v[226:227], s[52:53], 0, v[134:135]
	s_barrier
	ds_read_b128 v[166:169], v156 offset:16384
	ds_read_b128 v[178:181], v156 offset:17408
	ds_read_b128 v[182:185], v156 offset:18432
	ds_read_b128 v[186:189], v156 offset:19456
	ds_read_b128 v[190:193], v156 offset:20480
	ds_read_b128 v[194:197], v156 offset:21504
	ds_read_b128 v[198:201], v156 offset:22528
	ds_read_b128 v[202:205], v156 offset:23552
	global_load_lds_dwordx4 v[226:227], off
	v_lshl_add_u64 v[226:227], s[52:53], 0, v[130:131]
	s_mov_b32 m0, s59
	s_nop 0
	global_load_lds_dwordx4 v[226:227], off
	s_barrier
	s_waitcnt lgkmcnt(0)
	s_setprio 1
	s_waitcnt lgkmcnt(0)
	v_mfma_f32_16x16x32_bf16 v[60:63], v[144:147], v[166:169], v[60:63]
	v_mfma_f32_16x16x32_bf16 v[56:59], v[158:161], v[166:169], v[56:59]
	v_mfma_f32_16x16x32_bf16 v[44:47], v[144:147], v[182:185], v[44:47]
	v_mfma_f32_16x16x32_bf16 v[40:43], v[158:161], v[182:185], v[40:43]
	v_mfma_f32_16x16x32_bf16 v[28:31], v[144:147], v[190:193], v[28:31]
	v_mfma_f32_16x16x32_bf16 v[24:27], v[158:161], v[190:193], v[24:27]
	v_mfma_f32_16x16x32_bf16 v[12:15], v[144:147], v[198:201], v[12:15]
	v_mfma_f32_16x16x32_bf16 v[8:11], v[158:161], v[198:201], v[8:11]
	v_mfma_f32_16x16x32_bf16 v[60:63], v[148:151], v[178:181], v[60:63]
	v_mfma_f32_16x16x32_bf16 v[56:59], v[162:165], v[178:181], v[56:59]
	v_mfma_f32_16x16x32_bf16 v[44:47], v[148:151], v[186:189], v[44:47]
	v_mfma_f32_16x16x32_bf16 v[40:43], v[162:165], v[186:189], v[40:43]
	v_mfma_f32_16x16x32_bf16 v[28:31], v[148:151], v[194:197], v[28:31]
	v_mfma_f32_16x16x32_bf16 v[24:27], v[162:165], v[194:197], v[24:27]
	v_mfma_f32_16x16x32_bf16 v[12:15], v[148:151], v[202:205], v[12:15]
	v_mfma_f32_16x16x32_bf16 v[8:11], v[162:165], v[202:205], v[8:11]
	s_setprio 0
	s_barrier
	s_add_u32 s82, s48, 0x100000
	s_addc_u32 s83, s49, 0
	s_add_i32 s33, s69, s57
	v_lshl_add_u64 v[144:145], s[82:83], 0, v[132:133]
	s_mov_b32 m0, s33
	s_nop 0
	global_load_lds_dwordx4 v[144:145], off
	v_lshl_add_u64 v[144:145], s[82:83], 0, v[128:129]
	s_add_i32 m0, s33, 0x2000
	s_nop 0
	global_load_lds_dwordx4 v[144:145], off
	s_waitcnt vmcnt(6)
	s_barrier
	s_setprio 1
	v_mfma_f32_16x16x32_bf16 v[52:55], v[206:209], v[166:169], v[52:55]
	v_mfma_f32_16x16x32_bf16 v[48:51], v[214:217], v[166:169], v[48:51]
	v_mfma_f32_16x16x32_bf16 v[36:39], v[206:209], v[182:185], v[36:39]
	v_mfma_f32_16x16x32_bf16 v[32:35], v[214:217], v[182:185], v[32:35]
	v_mfma_f32_16x16x32_bf16 v[20:23], v[206:209], v[190:193], v[20:23]
	v_mfma_f32_16x16x32_bf16 v[16:19], v[214:217], v[190:193], v[16:19]
	v_mfma_f32_16x16x32_bf16 v[4:7], v[206:209], v[198:201], v[4:7]
	v_mfma_f32_16x16x32_bf16 v[0:3], v[214:217], v[198:201], v[0:3]
	v_mfma_f32_16x16x32_bf16 v[52:55], v[210:213], v[178:181], v[52:55]
	v_mfma_f32_16x16x32_bf16 v[48:51], v[218:221], v[178:181], v[48:51]
	v_mfma_f32_16x16x32_bf16 v[36:39], v[210:213], v[186:189], v[36:39]
	v_mfma_f32_16x16x32_bf16 v[32:35], v[218:221], v[186:189], v[32:35]
	v_mfma_f32_16x16x32_bf16 v[20:23], v[210:213], v[194:197], v[20:23]
	v_mfma_f32_16x16x32_bf16 v[16:19], v[218:221], v[194:197], v[16:19]
	v_mfma_f32_16x16x32_bf16 v[4:7], v[210:213], v[202:205], v[4:7]
	v_mfma_f32_16x16x32_bf16 v[0:3], v[218:221], v[202:205], v[0:3]
	s_setprio 0
	s_add_i32 s33, 0, 0x18000
	v_add_u32_e32 v162, s33, v153
	s_barrier
	ds_read_b128 v[144:147], v162
	ds_read_b128 v[148:151], v162 offset:1024
	ds_read_b128 v[158:161], v162 offset:2048
	ds_read_b128 v[162:165], v162 offset:3072
	s_add_u32 s52, s52, 0x4000
	s_addc_u32 s53, s53, 0
	s_mov_b32 m0, s60
	v_lshl_add_u64 v[206:207], s[52:53], 0, v[134:135]
	ds_read_b128 v[166:169], v156 offset:32768
	ds_read_b128 v[178:181], v156 offset:33792
	ds_read_b128 v[182:185], v156 offset:34816
	ds_read_b128 v[186:189], v156 offset:35840
	ds_read_b128 v[190:193], v156 offset:36864
	ds_read_b128 v[194:197], v156 offset:37888
	ds_read_b128 v[198:201], v156 offset:38912
	ds_read_b128 v[202:205], v156 offset:39936
	global_load_lds_dwordx4 v[206:207], off
	v_lshl_add_u64 v[206:207], s[52:53], 0, v[130:131]
	s_mov_b32 m0, s61
	s_nop 0
	global_load_lds_dwordx4 v[206:207], off
	s_waitcnt lgkmcnt(8)
	s_barrier
	s_waitcnt lgkmcnt(0)
	s_setprio 1
	s_waitcnt lgkmcnt(0)
	v_mfma_f32_16x16x32_bf16 v[124:127], v[144:147], v[166:169], v[124:127]
	v_mfma_f32_16x16x32_bf16 v[120:123], v[158:161], v[166:169], v[120:123]
	v_mfma_f32_16x16x32_bf16 v[108:111], v[144:147], v[182:185], v[108:111]
	v_mfma_f32_16x16x32_bf16 v[104:107], v[158:161], v[182:185], v[104:107]
	v_mfma_f32_16x16x32_bf16 v[92:95], v[144:147], v[190:193], v[92:95]
	v_mfma_f32_16x16x32_bf16 v[88:91], v[158:161], v[190:193], v[88:91]
	v_mfma_f32_16x16x32_bf16 v[76:79], v[144:147], v[198:201], v[76:79]
	v_mfma_f32_16x16x32_bf16 v[72:75], v[158:161], v[198:201], v[72:75]
	v_mfma_f32_16x16x32_bf16 v[124:127], v[148:151], v[178:181], v[124:127]
	v_mfma_f32_16x16x32_bf16 v[120:123], v[162:165], v[178:181], v[120:123]
	v_mfma_f32_16x16x32_bf16 v[108:111], v[148:151], v[186:189], v[108:111]
	v_mfma_f32_16x16x32_bf16 v[104:107], v[162:165], v[186:189], v[104:107]
	v_mfma_f32_16x16x32_bf16 v[92:95], v[148:151], v[194:197], v[92:95]
	v_mfma_f32_16x16x32_bf16 v[88:91], v[162:165], v[194:197], v[88:91]
	v_mfma_f32_16x16x32_bf16 v[76:79], v[148:151], v[202:205], v[76:79]
	v_mfma_f32_16x16x32_bf16 v[72:75], v[162:165], v[202:205], v[72:75]
	s_setprio 0
	s_barrier
	s_add_i32 s52, 0, 0x1c000
	s_add_i32 s33, s33, s57
	v_add_u32_e32 v177, s52, v153
	v_lshl_add_u64 v[222:223], v[222:223], 0, s[18:19]
	s_mov_b32 m0, s33
	ds_read_b128 v[206:209], v177
	ds_read_b128 v[210:213], v177 offset:1024
	ds_read_b128 v[214:217], v177 offset:2048
	ds_read_b128 v[218:221], v177 offset:3072
	global_load_lds_dwordx4 v[222:223], off
	v_lshl_add_u64 v[222:223], v[224:225], 0, s[18:19]
	s_add_i32 m0, s33, 0x2000
	s_nop 0
	global_load_lds_dwordx4 v[222:223], off
	s_barrier
	s_waitcnt lgkmcnt(0)
	s_setprio 1
	s_waitcnt lgkmcnt(0)
	v_mfma_f32_16x16x32_bf16 v[116:119], v[206:209], v[166:169], v[116:119]
	v_mfma_f32_16x16x32_bf16 v[112:115], v[214:217], v[166:169], v[112:115]
	v_mfma_f32_16x16x32_bf16 v[100:103], v[206:209], v[182:185], v[100:103]
	v_mfma_f32_16x16x32_bf16 v[96:99], v[214:217], v[182:185], v[96:99]
	v_mfma_f32_16x16x32_bf16 v[84:87], v[206:209], v[190:193], v[84:87]
	v_mfma_f32_16x16x32_bf16 v[80:83], v[214:217], v[190:193], v[80:83]
	v_mfma_f32_16x16x32_bf16 v[68:71], v[206:209], v[198:201], v[68:71]
	v_mfma_f32_16x16x32_bf16 v[64:67], v[214:217], v[198:201], v[64:67]
	v_mfma_f32_16x16x32_bf16 v[116:119], v[210:213], v[178:181], v[116:119]
	v_mfma_f32_16x16x32_bf16 v[112:115], v[218:221], v[178:181], v[112:115]
	v_mfma_f32_16x16x32_bf16 v[100:103], v[210:213], v[186:189], v[100:103]
	v_mfma_f32_16x16x32_bf16 v[96:99], v[218:221], v[186:189], v[96:99]
	v_mfma_f32_16x16x32_bf16 v[84:87], v[210:213], v[194:197], v[84:87]
	v_mfma_f32_16x16x32_bf16 v[80:83], v[218:221], v[194:197], v[80:83]
	v_mfma_f32_16x16x32_bf16 v[68:71], v[210:213], v[202:205], v[68:71]
	v_mfma_f32_16x16x32_bf16 v[64:67], v[218:221], v[202:205], v[64:67]
	s_setprio 0
	s_mov_b32 m0, s62
	v_lshl_add_u64 v[222:223], s[50:51], 0, v[134:135]
	s_barrier
	ds_read_b128 v[166:169], v156 offset:49152
	ds_read_b128 v[178:181], v156 offset:50176
	ds_read_b128 v[182:185], v156 offset:51200
	ds_read_b128 v[186:189], v156 offset:52224
	ds_read_b128 v[190:193], v156 offset:53248
	ds_read_b128 v[194:197], v156 offset:54272
	ds_read_b128 v[198:201], v156 offset:55296
	ds_read_b128 v[202:205], v156 offset:56320
	global_load_lds_dwordx4 v[222:223], off
	v_lshl_add_u64 v[222:223], s[50:51], 0, v[130:131]
	s_mov_b32 m0, s63
	s_nop 0
	global_load_lds_dwordx4 v[222:223], off
	s_barrier
	s_waitcnt lgkmcnt(0)
	s_setprio 1
	s_waitcnt lgkmcnt(0)
	v_mfma_f32_16x16x32_bf16 v[60:63], v[144:147], v[166:169], v[60:63]
	v_mfma_f32_16x16x32_bf16 v[56:59], v[158:161], v[166:169], v[56:59]
	v_mfma_f32_16x16x32_bf16 v[44:47], v[144:147], v[182:185], v[44:47]
	v_mfma_f32_16x16x32_bf16 v[40:43], v[158:161], v[182:185], v[40:43]
	v_mfma_f32_16x16x32_bf16 v[28:31], v[144:147], v[190:193], v[28:31]
	v_mfma_f32_16x16x32_bf16 v[24:27], v[158:161], v[190:193], v[24:27]
	v_mfma_f32_16x16x32_bf16 v[12:15], v[144:147], v[198:201], v[12:15]
	v_mfma_f32_16x16x32_bf16 v[8:11], v[158:161], v[198:201], v[8:11]
	v_mfma_f32_16x16x32_bf16 v[60:63], v[148:151], v[178:181], v[60:63]
	v_mfma_f32_16x16x32_bf16 v[56:59], v[162:165], v[178:181], v[56:59]
	v_mfma_f32_16x16x32_bf16 v[44:47], v[148:151], v[186:189], v[44:47]
	v_mfma_f32_16x16x32_bf16 v[40:43], v[162:165], v[186:189], v[40:43]
	v_mfma_f32_16x16x32_bf16 v[28:31], v[148:151], v[194:197], v[28:31]
	v_mfma_f32_16x16x32_bf16 v[24:27], v[162:165], v[194:197], v[24:27]
	v_mfma_f32_16x16x32_bf16 v[12:15], v[148:151], v[202:205], v[12:15]
	v_mfma_f32_16x16x32_bf16 v[8:11], v[162:165], v[202:205], v[8:11]
	s_setprio 0
	s_barrier
	s_add_u32 s48, s48, 0x100080
	s_addc_u32 s49, s49, 0
	s_add_i32 s33, s52, s57
	v_lshl_add_u64 v[144:145], s[48:49], 0, v[132:133]
	s_mov_b32 m0, s33
	s_nop 0
	global_load_lds_dwordx4 v[144:145], off
	v_lshl_add_u64 v[144:145], s[48:49], 0, v[128:129]
	s_add_i32 m0, s33, 0x2000
	s_nop 0
	global_load_lds_dwordx4 v[144:145], off
	s_waitcnt vmcnt(6)
	s_barrier
	s_setprio 1
	v_mfma_f32_16x16x32_bf16 v[52:55], v[206:209], v[166:169], v[52:55]
	v_mfma_f32_16x16x32_bf16 v[48:51], v[214:217], v[166:169], v[48:51]
	v_mfma_f32_16x16x32_bf16 v[36:39], v[206:209], v[182:185], v[36:39]
	v_mfma_f32_16x16x32_bf16 v[32:35], v[214:217], v[182:185], v[32:35]
	v_mfma_f32_16x16x32_bf16 v[20:23], v[206:209], v[190:193], v[20:23]
	v_mfma_f32_16x16x32_bf16 v[16:19], v[214:217], v[190:193], v[16:19]
	v_mfma_f32_16x16x32_bf16 v[4:7], v[206:209], v[198:201], v[4:7]
	v_mfma_f32_16x16x32_bf16 v[0:3], v[214:217], v[198:201], v[0:3]
	v_mfma_f32_16x16x32_bf16 v[52:55], v[210:213], v[178:181], v[52:55]
	v_mfma_f32_16x16x32_bf16 v[48:51], v[218:221], v[178:181], v[48:51]
	v_mfma_f32_16x16x32_bf16 v[36:39], v[210:213], v[186:189], v[36:39]
	v_mfma_f32_16x16x32_bf16 v[32:35], v[218:221], v[186:189], v[32:35]
	v_mfma_f32_16x16x32_bf16 v[20:23], v[210:213], v[194:197], v[20:23]
	v_mfma_f32_16x16x32_bf16 v[16:19], v[218:221], v[194:197], v[16:19]
	v_mfma_f32_16x16x32_bf16 v[4:7], v[210:213], v[202:205], v[4:7]
	v_mfma_f32_16x16x32_bf16 v[0:3], v[218:221], v[202:205], v[0:3]
	s_setprio 0
	s_add_i32 s80, s80, 2
	s_add_u32 s78, s78, 0x100
	s_addc_u32 s79, s79, 0
	s_add_u32 s40, s40, 0x10000
	s_addc_u32 s41, s41, 0
	s_cmp_gt_u32 s80, 61
	s_barrier
	s_cbranch_scc0 .LBB0_2049
	s_lshl_b32 s82, s10, 8
	v_lshl_or_b32 v145, s75, 8, v154
	v_add_u32_e32 v144, s82, v152
	v_lshlrev_b32_e32 v145, 2, v145
	s_sub_u32 s83, s82, 0x1000
	s_lshr_b32 s83, s83, 11
	s_mul_i32 s83, s83, 6
	s_add_i32 s83, s83, 41
	s_cmp_gt_i32 s10, 15
	s_cselect_b32 s83, s83, 35
	s_lshl_b32 s83, s83, 12
	s_add_u32 s50, s66, s83
	s_addc_u32 s51, s67, 0
	v_lshl_add_u32 v146, v144, 12, v145
	global_load_dwordx4 v[148:151], v145, s[50:51]
	global_load_dwordx4 v[158:161], v145, s[50:51] offset:64
	global_load_dwordx4 v[162:165], v145, s[50:51] offset:512
	global_load_dwordx4 v[166:169], v145, s[50:51] offset:576
	s_mov_b64 s[84:85], s[12:13]
	s_mov_b64 s[86:87], s[12:13]
	global_load_dwordx4 v[178:181], v146, s[84:85]
	global_load_dwordx4 v[182:185], v146, s[84:85] offset:64
	global_load_dwordx4 v[186:189], v146, s[84:85] offset:512
	global_load_dwordx4 v[190:193], v146, s[84:85] offset:576
	s_add_u32 s84, s84, 0x10000
	s_addc_u32 s85, s85, 0
	global_load_dwordx4 v[194:197], v146, s[84:85]
	global_load_dwordx4 v[198:201], v146, s[84:85] offset:64
	global_load_dwordx4 v[202:205], v146, s[84:85] offset:512
	global_load_dwordx4 v[206:209], v146, s[84:85] offset:576
	s_add_u32 s84, s84, 0x10000
	s_addc_u32 s85, s85, 0
	global_load_dwordx4 v[210:213], v146, s[84:85]
	global_load_dwordx4 v[214:217], v146, s[84:85] offset:64
	global_load_dwordx4 v[218:221], v146, s[84:85] offset:512
	global_load_dwordx4 v[222:225], v146, s[84:85] offset:576
	s_add_u32 s84, s84, 0x10000
	s_addc_u32 s85, s85, 0
	global_load_dwordx4 v[226:229], v146, s[84:85]
	global_load_dwordx4 v[230:233], v146, s[84:85] offset:64
	s_waitcnt vmcnt(13)
	v_pk_fma_f32 v[124:125], v[124:125], v[148:149], v[178:179]
	v_pk_fma_f32 v[126:127], v[126:127], v[150:151], v[180:181]
	global_store_dwordx4 v146, v[124:127], s[86:87]
	global_load_dwordx4 v[178:181], v146, s[84:85] offset:512
	s_waitcnt vmcnt(14)
	v_pk_fma_f32 v[120:121], v[120:121], v[158:159], v[182:183]
	v_pk_fma_f32 v[122:123], v[122:123], v[160:161], v[184:185]
	global_store_dwordx4 v146, v[120:123], s[86:87] offset:64
	global_load_dwordx4 v[182:185], v146, s[84:85] offset:576
	s_waitcnt vmcnt(15)
	v_pk_fma_f32 v[116:117], v[116:117], v[162:163], v[186:187]
	v_pk_fma_f32 v[118:119], v[118:119], v[164:165], v[188:189]
	global_store_dwordx4 v146, v[116:119], s[86:87] offset:512
	s_add_u32 s84, s84, 0x50000
	s_addc_u32 s85, s85, 0
	global_load_dwordx4 v[186:189], v146, s[84:85]
	s_waitcnt vmcnt(16)
	v_pk_fma_f32 v[112:113], v[112:113], v[166:167], v[190:191]
	v_pk_fma_f32 v[114:115], v[114:115], v[168:169], v[192:193]
	global_store_dwordx4 v146, v[112:115], s[86:87] offset:576
	global_load_dwordx4 v[190:193], v146, s[84:85] offset:64
	s_add_u32 s86, s86, 0x10000
	s_addc_u32 s87, s87, 0
	s_waitcnt vmcnt(17)
	v_pk_fma_f32 v[108:109], v[108:109], v[148:149], v[194:195]
	v_pk_fma_f32 v[110:111], v[110:111], v[150:151], v[196:197]
	global_store_dwordx4 v146, v[108:111], s[86:87]
	global_load_dwordx4 v[194:197], v146, s[84:85] offset:512
	s_waitcnt vmcnt(18)
	v_pk_fma_f32 v[104:105], v[104:105], v[158:159], v[198:199]
	v_pk_fma_f32 v[106:107], v[106:107], v[160:161], v[200:201]
	global_store_dwordx4 v146, v[104:107], s[86:87] offset:64
	global_load_dwordx4 v[198:201], v146, s[84:85] offset:576
	s_waitcnt vmcnt(19)
	v_pk_fma_f32 v[100:101], v[100:101], v[162:163], v[202:203]
	v_pk_fma_f32 v[102:103], v[102:103], v[164:165], v[204:205]
	global_store_dwordx4 v146, v[100:103], s[86:87] offset:512
	s_add_u32 s84, s84, 0x10000
	s_addc_u32 s85, s85, 0
	global_load_dwordx4 v[202:205], v146, s[84:85]
	s_waitcnt vmcnt(20)
	v_pk_fma_f32 v[96:97], v[96:97], v[166:167], v[206:207]
	v_pk_fma_f32 v[98:99], v[98:99], v[168:169], v[208:209]
	global_store_dwordx4 v146, v[96:99], s[86:87] offset:576
	global_load_dwordx4 v[206:209], v146, s[84:85] offset:64
	s_add_u32 s86, s86, 0x10000
	s_addc_u32 s87, s87, 0
	s_waitcnt vmcnt(21)
	v_pk_fma_f32 v[92:93], v[92:93], v[148:149], v[210:211]
	v_pk_fma_f32 v[94:95], v[94:95], v[150:151], v[212:213]
	global_store_dwordx4 v146, v[92:95], s[86:87]
	global_load_dwordx4 v[210:213], v146, s[84:85] offset:512
	s_waitcnt vmcnt(22)
	v_pk_fma_f32 v[88:89], v[88:89], v[158:159], v[214:215]
	v_pk_fma_f32 v[90:91], v[90:91], v[160:161], v[216:217]
	global_store_dwordx4 v146, v[88:91], s[86:87] offset:64
	global_load_dwordx4 v[214:217], v146, s[84:85] offset:576
	s_waitcnt vmcnt(23)
	v_pk_fma_f32 v[84:85], v[84:85], v[162:163], v[218:219]
	v_pk_fma_f32 v[86:87], v[86:87], v[164:165], v[220:221]
	global_store_dwordx4 v146, v[84:87], s[86:87] offset:512
	s_add_u32 s84, s84, 0x10000
	s_addc_u32 s85, s85, 0
	global_load_dwordx4 v[218:221], v146, s[84:85]
	s_waitcnt vmcnt(24)
	v_pk_fma_f32 v[80:81], v[80:81], v[166:167], v[222:223]
	v_pk_fma_f32 v[82:83], v[82:83], v[168:169], v[224:225]
	global_store_dwordx4 v146, v[80:83], s[86:87] offset:576
	global_load_dwordx4 v[222:225], v146, s[84:85] offset:64
	s_add_u32 s86, s86, 0x10000
	s_addc_u32 s87, s87, 0
	s_waitcnt vmcnt(25)
	v_pk_fma_f32 v[76:77], v[76:77], v[148:149], v[226:227]
	v_pk_fma_f32 v[78:79], v[78:79], v[150:151], v[228:229]
	global_store_dwordx4 v146, v[76:79], s[86:87]
	global_load_dwordx4 v[226:229], v146, s[84:85] offset:512
	s_waitcnt vmcnt(26)
	v_pk_fma_f32 v[72:73], v[72:73], v[158:159], v[230:231]
	v_pk_fma_f32 v[74:75], v[74:75], v[160:161], v[232:233]
	global_store_dwordx4 v146, v[72:75], s[86:87] offset:64
	global_load_dwordx4 v[230:233], v146, s[84:85] offset:576
	s_waitcnt vmcnt(26)
	v_pk_fma_f32 v[68:69], v[68:69], v[162:163], v[178:179]
	v_pk_fma_f32 v[70:71], v[70:71], v[164:165], v[180:181]
	global_store_dwordx4 v146, v[68:71], s[86:87] offset:512
	s_add_u32 s84, s84, 0x10000
	s_addc_u32 s85, s85, 0
	global_load_dwordx4 v[178:181], v146, s[84:85]
	s_waitcnt vmcnt(26)
	v_pk_fma_f32 v[64:65], v[64:65], v[166:167], v[182:183]
	v_pk_fma_f32 v[66:67], v[66:67], v[168:169], v[184:185]
	global_store_dwordx4 v146, v[64:67], s[86:87] offset:576
	global_load_dwordx4 v[182:185], v146, s[84:85] offset:64
	s_add_u32 s86, s86, 0x50000
	s_addc_u32 s87, s87, 0
	s_waitcnt vmcnt(26)
	v_pk_fma_f32 v[60:61], v[60:61], v[148:149], v[186:187]
	v_pk_fma_f32 v[62:63], v[62:63], v[150:151], v[188:189]
	global_store_dwordx4 v146, v[60:63], s[86:87]
	global_load_dwordx4 v[186:189], v146, s[84:85] offset:512
	s_waitcnt vmcnt(26)
	v_pk_fma_f32 v[56:57], v[56:57], v[158:159], v[190:191]
	v_pk_fma_f32 v[58:59], v[58:59], v[160:161], v[192:193]
	global_store_dwordx4 v146, v[56:59], s[86:87] offset:64
	global_load_dwordx4 v[190:193], v146, s[84:85] offset:576
	s_waitcnt vmcnt(26)
	v_pk_fma_f32 v[52:53], v[52:53], v[162:163], v[194:195]
	v_pk_fma_f32 v[54:55], v[54:55], v[164:165], v[196:197]
	global_store_dwordx4 v146, v[52:55], s[86:87] offset:512
	s_waitcnt vmcnt(25)
	v_pk_fma_f32 v[48:49], v[48:49], v[166:167], v[198:199]
	v_pk_fma_f32 v[50:51], v[50:51], v[168:169], v[200:201]
	global_store_dwordx4 v146, v[48:51], s[86:87] offset:576
	s_add_u32 s86, s86, 0x10000
	s_addc_u32 s87, s87, 0
	s_waitcnt vmcnt(24)
	v_pk_fma_f32 v[44:45], v[44:45], v[148:149], v[202:203]
	v_pk_fma_f32 v[46:47], v[46:47], v[150:151], v[204:205]
	global_store_dwordx4 v146, v[44:47], s[86:87]
	s_waitcnt vmcnt(23)
	v_pk_fma_f32 v[40:41], v[40:41], v[158:159], v[206:207]
	v_pk_fma_f32 v[42:43], v[42:43], v[160:161], v[208:209]
	global_store_dwordx4 v146, v[40:43], s[86:87] offset:64
	s_waitcnt vmcnt(22)
	v_pk_fma_f32 v[36:37], v[36:37], v[162:163], v[210:211]
	v_pk_fma_f32 v[38:39], v[38:39], v[164:165], v[212:213]
	global_store_dwordx4 v146, v[36:39], s[86:87] offset:512
	s_waitcnt vmcnt(21)
	v_pk_fma_f32 v[32:33], v[32:33], v[166:167], v[214:215]
	v_pk_fma_f32 v[34:35], v[34:35], v[168:169], v[216:217]
	global_store_dwordx4 v146, v[32:35], s[86:87] offset:576
	s_add_u32 s86, s86, 0x10000
	s_addc_u32 s87, s87, 0
	s_waitcnt vmcnt(20)
	v_pk_fma_f32 v[28:29], v[28:29], v[148:149], v[218:219]
	v_pk_fma_f32 v[30:31], v[30:31], v[150:151], v[220:221]
	global_store_dwordx4 v146, v[28:31], s[86:87]
	s_waitcnt vmcnt(19)
	v_pk_fma_f32 v[24:25], v[24:25], v[158:159], v[222:223]
	v_pk_fma_f32 v[26:27], v[26:27], v[160:161], v[224:225]
	global_store_dwordx4 v146, v[24:27], s[86:87] offset:64
	s_waitcnt vmcnt(18)
	v_pk_fma_f32 v[20:21], v[20:21], v[162:163], v[226:227]
	v_pk_fma_f32 v[22:23], v[22:23], v[164:165], v[228:229]
	global_store_dwordx4 v146, v[20:23], s[86:87] offset:512
	s_waitcnt vmcnt(17)
	v_pk_fma_f32 v[16:17], v[16:17], v[166:167], v[230:231]
	v_pk_fma_f32 v[18:19], v[18:19], v[168:169], v[232:233]
	global_store_dwordx4 v146, v[16:19], s[86:87] offset:576
	s_add_u32 s86, s86, 0x10000
	s_addc_u32 s87, s87, 0
	s_waitcnt vmcnt(16)
	v_pk_fma_f32 v[12:13], v[12:13], v[148:149], v[178:179]
	v_pk_fma_f32 v[14:15], v[14:15], v[150:151], v[180:181]
	global_store_dwordx4 v146, v[12:15], s[86:87]
	s_waitcnt vmcnt(15)
	v_pk_fma_f32 v[8:9], v[8:9], v[158:159], v[182:183]
	v_pk_fma_f32 v[10:11], v[10:11], v[160:161], v[184:185]
	global_store_dwordx4 v146, v[8:11], s[86:87] offset:64
	s_waitcnt vmcnt(14)
	v_pk_fma_f32 v[4:5], v[4:5], v[162:163], v[186:187]
	v_pk_fma_f32 v[6:7], v[6:7], v[164:165], v[188:189]
	global_store_dwordx4 v146, v[4:7], s[86:87] offset:512
	s_waitcnt vmcnt(13)
	v_pk_fma_f32 v[0:1], v[0:1], v[166:167], v[190:191]
	v_pk_fma_f32 v[2:3], v[2:3], v[168:169], v[192:193]
	global_store_dwordx4 v146, v[0:3], s[86:87] offset:576
	s_mov_b32 s75, s28
	s_mov_b64 s[40:41], s[36:37]
	s_mov_b64 s[48:49], s[34:35]
	s_mov_b32 s10, s30
	s_and_b64 vcc, exec, s[8:9]
	s_cbranch_vccz .LBB0_2046
	s_waitcnt vmcnt(0)
	s_cmpk_gt_u32 s45, 0xff
	s_cbranch_scc1 .LBB0_2053
	s_barrier
